# GEMM-down epilogue fused with the final rmsnorm by hand: x stays in the accumulators, row sums of squares via LDS + a partial table, one grid barrier, y stored once (the final-norm phase and its barri
# speedup vs baseline: 1.1605x; 1.0247x over previous
.Lrb1_helper:
	s_sub_u32 s6, s0, 4
	s_lshl_b32 s6, s6, 10
	s_lshl_b32 s7, s5, 12
	s_add_u32 s6, s6, s7
	s_add_u32 s6, s6, 0x2c000
	v_lshl_add_u32 v40, v2, 4, s6
	s_movk_i32 s10, 58

.LBB0_1435:
	s_waitcnt vmcnt(0) lgkmcnt(0)
	s_mov_b64 s[38:39], exec
	v_mov_b32_e32 v204, 0x40135761
	v_mov_b32_e32 v205, 0x40135761
	v_mov_b32_e32 v206, 0x3dd2d3e8
	v_mov_b32_e32 v207, 0x3dd2d3e8
	v_and_b32_e32 v200, 0xff, v172
	v_mad_u32_u24 v197, v172, s15, v199
	v_cmp_ne_u32_e64 s[86:87], 0, v200
	v_cmp_ne_u32_e64 s[88:89], s16, v200
	global_load_dwordx4 v[96:99], v197, s[60:61]
	global_load_dwordx4 v[152:155], v197, s[96:97]
	v_subrev_u32_e32 v201, 0x1600, v197
	v_add_u32_e32 v202, 0x1600, v197
	v_cndmask_b32_e64 v201, v197, v201, s[86:87]
	v_cndmask_b32_e64 v202, v197, v202, s[88:89]
	global_load_dwordx4 v[92:95], v201, s[60:61]
	global_load_dwordx4 v[100:103], v202, s[60:61]
	v_add_u32_e32 v172, s12, v172
	v_and_b32_e32 v200, 0xff, v172
	v_mad_u32_u24 v198, v172, s15, v199
	v_cmp_ne_u32_e64 s[50:51], 0, v200
	v_cmp_ne_u32_e64 s[52:53], s16, v200
	global_load_dwordx4 v[132:135], v198, s[60:61]
	global_load_dwordx4 v[156:159], v198, s[96:97]
	v_subrev_u32_e32 v201, 0x1600, v198
	v_add_u32_e32 v202, 0x1600, v198
	v_cndmask_b32_e64 v201, v198, v201, s[50:51]
	v_cndmask_b32_e64 v202, v198, v202, s[52:53]
	global_load_dwordx4 v[128:131], v201, s[60:61]
	global_load_dwordx4 v[136:139], v202, s[60:61]
	v_add_u32_e32 v172, s12, v172
	s_waitcnt vmcnt(4)
	v_lshlrev_b32_e32 v216, 16, v96
	v_and_b32_e32 v217, 0xffff0000, v96
	v_lshlrev_b32_e32 v218, 16, v97
	v_and_b32_e32 v219, 0xffff0000, v97
	v_lshlrev_b32_e32 v220, 16, v98
	v_and_b32_e32 v221, 0xffff0000, v98
	v_lshlrev_b32_e32 v222, 16, v99
	v_and_b32_e32 v223, 0xffff0000, v99
	v_fma_f32 v208, v32, v216, v72
	v_fma_f32 v209, v33, v217, v73
	v_fma_f32 v210, v34, v218, v74
	v_fma_f32 v211, v35, v219, v75
	v_fma_f32 v212, v36, v220, v76
	v_fma_f32 v213, v37, v221, v77
	v_fma_f32 v214, v38, v222, v78
	v_fma_f32 v215, v39, v223, v79
	s_mov_b64 exec, s[86:87]
	s_cbranch_execz .Lact_t1_k3
	v_lshlrev_b32_e32 v216, 16, v92
	v_and_b32_e32 v217, 0xffff0000, v92
	v_lshlrev_b32_e32 v218, 16, v93
	v_and_b32_e32 v219, 0xffff0000, v93
	v_lshlrev_b32_e32 v220, 16, v94
	v_and_b32_e32 v221, 0xffff0000, v94
	v_lshlrev_b32_e32 v222, 16, v95
	v_and_b32_e32 v223, 0xffff0000, v95
	v_fmac_f32_e32 v208, v24, v216
	v_fmac_f32_e32 v209, v25, v217
	v_fmac_f32_e32 v210, v26, v218
	v_fmac_f32_e32 v211, v27, v219
	v_fmac_f32_e32 v212, v28, v220
	v_fmac_f32_e32 v213, v29, v221
	v_fmac_f32_e32 v214, v30, v222
	v_fmac_f32_e32 v215, v31, v223

.Lact_t1_k5:
	s_mov_b64 exec, s[38:39]
	v_mul_f32_e32 v216, v208, v208
	v_mul_f32_e32 v217, v209, v209
	v_mul_f32_e32 v218, v210, v210
	v_mul_f32_e32 v219, v211, v211
	v_mul_f32_e32 v220, v212, v212
	v_mul_f32_e32 v221, v213, v213
	v_mul_f32_e32 v222, v214, v214
	v_mul_f32_e32 v223, v215, v215
	v_fmamk_f32 v216, v216, 0x3dd2d3e8, v204
	v_fmamk_f32 v217, v217, 0x3dd2d3e8, v204
	v_fmamk_f32 v218, v218, 0x3dd2d3e8, v204
	v_fmamk_f32 v219, v219, 0x3dd2d3e8, v204
	v_fmamk_f32 v220, v220, 0x3dd2d3e8, v204
	v_fmamk_f32 v221, v221, 0x3dd2d3e8, v204
	v_fmamk_f32 v222, v222, 0x3dd2d3e8, v204
	v_fmamk_f32 v223, v223, 0x3dd2d3e8, v204
	v_mul_f32_e32 v216, v216, v208
	v_mul_f32_e32 v217, v217, v209
	v_mul_f32_e32 v218, v218, v210
	v_mul_f32_e32 v219, v219, v211
	v_mul_f32_e32 v220, v220, v212
	v_mul_f32_e32 v221, v221, v213
	v_mul_f32_e32 v222, v222, v214
	v_mul_f32_e32 v223, v223, v215
	v_exp_f32_e32 v216, v216
	v_exp_f32_e32 v217, v217
	v_exp_f32_e32 v218, v218
	v_exp_f32_e32 v219, v219
	v_exp_f32_e32 v220, v220
	v_exp_f32_e32 v221, v221
	v_exp_f32_e32 v222, v222
	v_exp_f32_e32 v223, v223
	v_lshlrev_b32_e32 v224, 16, v152
	v_and_b32_e32 v225, 0xffff0000, v152
	v_lshlrev_b32_e32 v226, 16, v153
	v_and_b32_e32 v227, 0xffff0000, v153
	v_lshlrev_b32_e32 v228, 16, v154
	v_and_b32_e32 v229, 0xffff0000, v154
	v_lshlrev_b32_e32 v230, 16, v155
	v_and_b32_e32 v231, 0xffff0000, v155
	v_add_f32_e32 v216, 1.0, v216
	v_add_f32_e32 v217, 1.0, v217
	v_add_f32_e32 v218, 1.0, v218
	v_add_f32_e32 v219, 1.0, v219
	v_add_f32_e32 v220, 1.0, v220
	v_add_f32_e32 v221, 1.0, v221
	v_add_f32_e32 v222, 1.0, v222
	v_add_f32_e32 v223, 1.0, v223
	v_rcp_f32_e32 v216, v216
	v_rcp_f32_e32 v217, v217
	v_rcp_f32_e32 v218, v218
	v_rcp_f32_e32 v219, v219
	v_rcp_f32_e32 v220, v220
	v_rcp_f32_e32 v221, v221
	v_rcp_f32_e32 v222, v222
	v_rcp_f32_e32 v223, v223
	s_nop 0
	v_fma_f32 v216, -v208, v216, v208
	v_fma_f32 v217, -v209, v217, v209
	v_fma_f32 v218, -v210, v218, v210
	v_fma_f32 v219, -v211, v219, v211
	v_fma_f32 v220, -v212, v220, v212
	v_fma_f32 v221, -v213, v221, v213
	v_fma_f32 v222, -v214, v222, v214
	v_fma_f32 v223, -v215, v223, v215
	v_mul_f32_e32 v216, v216, v224
	v_mul_f32_e32 v217, v217, v225
	v_mul_f32_e32 v218, v218, v226
	v_mul_f32_e32 v219, v219, v227
	v_mul_f32_e32 v220, v220, v228
	v_mul_f32_e32 v221, v221, v229
	v_mul_f32_e32 v222, v222, v230
	v_mul_f32_e32 v223, v223, v231
	v_cvt_pk_bf16_f32 v208, v216, v217
	v_cvt_pk_bf16_f32 v209, v218, v219
	v_cvt_pk_bf16_f32 v210, v220, v221
	v_cvt_pk_bf16_f32 v211, v222, v223
	global_store_dwordx4 v197, v[208:211], s[96:97] sc1
	s_movk_i32 s8, 10

.Lact_t2_k5:
	s_mov_b64 exec, s[38:39]
	v_mul_f32_e32 v216, v208, v208
	v_mul_f32_e32 v217, v209, v209
	v_mul_f32_e32 v218, v210, v210
	v_mul_f32_e32 v219, v211, v211
	v_mul_f32_e32 v220, v212, v212
	v_mul_f32_e32 v221, v213, v213
	v_mul_f32_e32 v222, v214, v214
	v_mul_f32_e32 v223, v215, v215
	v_fmamk_f32 v216, v216, 0x3dd2d3e8, v204
	v_fmamk_f32 v217, v217, 0x3dd2d3e8, v204
	v_fmamk_f32 v218, v218, 0x3dd2d3e8, v204
	v_fmamk_f32 v219, v219, 0x3dd2d3e8, v204
	v_fmamk_f32 v220, v220, 0x3dd2d3e8, v204
	v_fmamk_f32 v221, v221, 0x3dd2d3e8, v204
	v_fmamk_f32 v222, v222, 0x3dd2d3e8, v204
	v_fmamk_f32 v223, v223, 0x3dd2d3e8, v204
	v_mul_f32_e32 v216, v216, v208
	v_mul_f32_e32 v217, v217, v209
	v_mul_f32_e32 v218, v218, v210
	v_mul_f32_e32 v219, v219, v211
	v_mul_f32_e32 v220, v220, v212
	v_mul_f32_e32 v221, v221, v213
	v_mul_f32_e32 v222, v222, v214
	v_mul_f32_e32 v223, v223, v215
	v_exp_f32_e32 v216, v216
	v_exp_f32_e32 v217, v217
	v_exp_f32_e32 v218, v218
	v_exp_f32_e32 v219, v219
	v_exp_f32_e32 v220, v220
	v_exp_f32_e32 v221, v221
	v_exp_f32_e32 v222, v222
	v_exp_f32_e32 v223, v223
	v_lshlrev_b32_e32 v224, 16, v156
	v_and_b32_e32 v225, 0xffff0000, v156
	v_lshlrev_b32_e32 v226, 16, v157
	v_and_b32_e32 v227, 0xffff0000, v157
	v_lshlrev_b32_e32 v228, 16, v158
	v_and_b32_e32 v229, 0xffff0000, v158
	v_lshlrev_b32_e32 v230, 16, v159
	v_and_b32_e32 v231, 0xffff0000, v159
	v_add_f32_e32 v216, 1.0, v216
	v_add_f32_e32 v217, 1.0, v217
	v_add_f32_e32 v218, 1.0, v218
	v_add_f32_e32 v219, 1.0, v219
	v_add_f32_e32 v220, 1.0, v220
	v_add_f32_e32 v221, 1.0, v221
	v_add_f32_e32 v222, 1.0, v222
	v_add_f32_e32 v223, 1.0, v223
	v_rcp_f32_e32 v216, v216
	v_rcp_f32_e32 v217, v217
	v_rcp_f32_e32 v218, v218
	v_rcp_f32_e32 v219, v219
	v_rcp_f32_e32 v220, v220
	v_rcp_f32_e32 v221, v221
	v_rcp_f32_e32 v222, v222
	v_rcp_f32_e32 v223, v223
	s_nop 0
	v_fma_f32 v216, -v208, v216, v208
	v_fma_f32 v217, -v209, v217, v209
	v_fma_f32 v218, -v210, v218, v210
	v_fma_f32 v219, -v211, v219, v211
	v_fma_f32 v220, -v212, v220, v212
	v_fma_f32 v221, -v213, v221, v213
	v_fma_f32 v222, -v214, v222, v214
	v_fma_f32 v223, -v215, v223, v215
	v_mul_f32_e32 v216, v216, v224
	v_mul_f32_e32 v217, v217, v225
	v_mul_f32_e32 v218, v218, v226
	v_mul_f32_e32 v219, v219, v227
	v_mul_f32_e32 v220, v220, v228
	v_mul_f32_e32 v221, v221, v229
	v_mul_f32_e32 v222, v222, v230
	v_mul_f32_e32 v223, v223, v231
	v_cvt_pk_bf16_f32 v208, v216, v217
	v_cvt_pk_bf16_f32 v209, v218, v219
	v_cvt_pk_bf16_f32 v210, v220, v221
	v_cvt_pk_bf16_f32 v211, v222, v223
	global_store_dwordx4 v198, v[208:211], s[96:97] sc1
	v_and_b32_e32 v200, 0xff, v172
	v_mad_u32_u24 v198, v172, s15, v199
	v_cmp_ne_u32_e64 s[50:51], 0, v200
	v_cmp_ne_u32_e64 s[52:53], s16, v200
	global_load_dwordx4 v[132:135], v198, s[60:61]
	global_load_dwordx4 v[156:159], v198, s[96:97]
	v_subrev_u32_e32 v201, 0x1600, v198
	v_add_u32_e32 v202, 0x1600, v198
	v_cndmask_b32_e64 v201, v198, v201, s[50:51]
	v_cndmask_b32_e64 v202, v198, v202, s[52:53]
	global_load_dwordx4 v[128:131], v201, s[60:61]
	global_load_dwordx4 v[136:139], v202, s[60:61]
	v_add_u32_e32 v172, s12, v172
	s_waitcnt vmcnt(5)
	v_lshlrev_b32_e32 v216, 16, v96
	v_and_b32_e32 v217, 0xffff0000, v96
	v_lshlrev_b32_e32 v218, 16, v97
	v_and_b32_e32 v219, 0xffff0000, v97
	v_lshlrev_b32_e32 v220, 16, v98
	v_and_b32_e32 v221, 0xffff0000, v98
	v_lshlrev_b32_e32 v222, 16, v99
	v_and_b32_e32 v223, 0xffff0000, v99
	v_fma_f32 v208, v32, v216, v72
	v_fma_f32 v209, v33, v217, v73
	v_fma_f32 v210, v34, v218, v74
	v_fma_f32 v211, v35, v219, v75
	v_fma_f32 v212, v36, v220, v76
	v_fma_f32 v213, v37, v221, v77
	v_fma_f32 v214, v38, v222, v78
	v_fma_f32 v215, v39, v223, v79
	s_mov_b64 exec, s[86:87]
	s_cbranch_execz .Lact_t3_k3
	v_lshlrev_b32_e32 v216, 16, v92
	v_and_b32_e32 v217, 0xffff0000, v92
	v_lshlrev_b32_e32 v218, 16, v93
	v_and_b32_e32 v219, 0xffff0000, v93
	v_lshlrev_b32_e32 v220, 16, v94
	v_and_b32_e32 v221, 0xffff0000, v94
	v_lshlrev_b32_e32 v222, 16, v95
	v_and_b32_e32 v223, 0xffff0000, v95
	v_fmac_f32_e32 v208, v24, v216
	v_fmac_f32_e32 v209, v25, v217
	v_fmac_f32_e32 v210, v26, v218
	v_fmac_f32_e32 v211, v27, v219
	v_fmac_f32_e32 v212, v28, v220
	v_fmac_f32_e32 v213, v29, v221
	v_fmac_f32_e32 v214, v30, v222
	v_fmac_f32_e32 v215, v31, v223

.Lact_t3_k5:
	s_mov_b64 exec, s[38:39]
	v_mul_f32_e32 v216, v208, v208
	v_mul_f32_e32 v217, v209, v209
	v_mul_f32_e32 v218, v210, v210
	v_mul_f32_e32 v219, v211, v211
	v_mul_f32_e32 v220, v212, v212
	v_mul_f32_e32 v221, v213, v213
	v_mul_f32_e32 v222, v214, v214
	v_mul_f32_e32 v223, v215, v215
	v_fmamk_f32 v216, v216, 0x3dd2d3e8, v204
	v_fmamk_f32 v217, v217, 0x3dd2d3e8, v204
	v_fmamk_f32 v218, v218, 0x3dd2d3e8, v204
	v_fmamk_f32 v219, v219, 0x3dd2d3e8, v204
	v_fmamk_f32 v220, v220, 0x3dd2d3e8, v204
	v_fmamk_f32 v221, v221, 0x3dd2d3e8, v204
	v_fmamk_f32 v222, v222, 0x3dd2d3e8, v204
	v_fmamk_f32 v223, v223, 0x3dd2d3e8, v204
	v_mul_f32_e32 v216, v216, v208
	v_mul_f32_e32 v217, v217, v209
	v_mul_f32_e32 v218, v218, v210
	v_mul_f32_e32 v219, v219, v211
	v_mul_f32_e32 v220, v220, v212
	v_mul_f32_e32 v221, v221, v213
	v_mul_f32_e32 v222, v222, v214
	v_mul_f32_e32 v223, v223, v215
	v_exp_f32_e32 v216, v216
	v_exp_f32_e32 v217, v217
	v_exp_f32_e32 v218, v218
	v_exp_f32_e32 v219, v219
	v_exp_f32_e32 v220, v220
	v_exp_f32_e32 v221, v221
	v_exp_f32_e32 v222, v222
	v_exp_f32_e32 v223, v223
	v_lshlrev_b32_e32 v224, 16, v152
	v_and_b32_e32 v225, 0xffff0000, v152
	v_lshlrev_b32_e32 v226, 16, v153
	v_and_b32_e32 v227, 0xffff0000, v153
	v_lshlrev_b32_e32 v228, 16, v154
	v_and_b32_e32 v229, 0xffff0000, v154
	v_lshlrev_b32_e32 v230, 16, v155
	v_and_b32_e32 v231, 0xffff0000, v155
	v_add_f32_e32 v216, 1.0, v216
	v_add_f32_e32 v217, 1.0, v217
	v_add_f32_e32 v218, 1.0, v218
	v_add_f32_e32 v219, 1.0, v219
	v_add_f32_e32 v220, 1.0, v220
	v_add_f32_e32 v221, 1.0, v221
	v_add_f32_e32 v222, 1.0, v222
	v_add_f32_e32 v223, 1.0, v223
	v_rcp_f32_e32 v216, v216
	v_rcp_f32_e32 v217, v217
	v_rcp_f32_e32 v218, v218
	v_rcp_f32_e32 v219, v219
	v_rcp_f32_e32 v220, v220
	v_rcp_f32_e32 v221, v221
	v_rcp_f32_e32 v222, v222
	v_rcp_f32_e32 v223, v223
	s_nop 0
	v_fma_f32 v216, -v208, v216, v208
	v_fma_f32 v217, -v209, v217, v209
	v_fma_f32 v218, -v210, v218, v210
	v_fma_f32 v219, -v211, v219, v211
	v_fma_f32 v220, -v212, v220, v212
	v_fma_f32 v221, -v213, v221, v213
	v_fma_f32 v222, -v214, v222, v214
	v_fma_f32 v223, -v215, v223, v215
	v_mul_f32_e32 v216, v216, v224
	v_mul_f32_e32 v217, v217, v225
	v_mul_f32_e32 v218, v218, v226
	v_mul_f32_e32 v219, v219, v227
	v_mul_f32_e32 v220, v220, v228
	v_mul_f32_e32 v221, v221, v229
	v_mul_f32_e32 v222, v222, v230
	v_mul_f32_e32 v223, v223, v231
	v_cvt_pk_bf16_f32 v208, v216, v217
	v_cvt_pk_bf16_f32 v209, v218, v219
	v_cvt_pk_bf16_f32 v210, v220, v221
	v_cvt_pk_bf16_f32 v211, v222, v223
	global_store_dwordx4 v197, v[208:211], s[96:97] sc1
	s_sub_u32 s8, s8, 1
	s_cmp_lg_u32 s8, 0
	s_cbranch_scc1 .Lact_ctx_loop
	s_waitcnt vmcnt(1)
	v_lshlrev_b32_e32 v216, 16, v132
	v_and_b32_e32 v217, 0xffff0000, v132
	v_lshlrev_b32_e32 v218, 16, v133
	v_and_b32_e32 v219, 0xffff0000, v133
	v_lshlrev_b32_e32 v220, 16, v134
	v_and_b32_e32 v221, 0xffff0000, v134
	v_lshlrev_b32_e32 v222, 16, v135
	v_and_b32_e32 v223, 0xffff0000, v135
	v_fma_f32 v208, v32, v216, v72
	v_fma_f32 v209, v33, v217, v73
	v_fma_f32 v210, v34, v218, v74
	v_fma_f32 v211, v35, v219, v75
	v_fma_f32 v212, v36, v220, v76
	v_fma_f32 v213, v37, v221, v77
	v_fma_f32 v214, v38, v222, v78
	v_fma_f32 v215, v39, v223, v79
	s_mov_b64 exec, s[50:51]
	s_cbranch_execz .Lact_t4_k3
	v_lshlrev_b32_e32 v216, 16, v128
	v_and_b32_e32 v217, 0xffff0000, v128
	v_lshlrev_b32_e32 v218, 16, v129
	v_and_b32_e32 v219, 0xffff0000, v129
	v_lshlrev_b32_e32 v220, 16, v130
	v_and_b32_e32 v221, 0xffff0000, v130
	v_lshlrev_b32_e32 v222, 16, v131
	v_and_b32_e32 v223, 0xffff0000, v131
	v_fmac_f32_e32 v208, v24, v216
	v_fmac_f32_e32 v209, v25, v217
	v_fmac_f32_e32 v210, v26, v218
	v_fmac_f32_e32 v211, v27, v219
	v_fmac_f32_e32 v212, v28, v220
	v_fmac_f32_e32 v213, v29, v221
	v_fmac_f32_e32 v214, v30, v222
	v_fmac_f32_e32 v215, v31, v223

.Lact_t4_k5:
	s_mov_b64 exec, s[38:39]
	v_mul_f32_e32 v216, v208, v208
	v_mul_f32_e32 v217, v209, v209
	v_mul_f32_e32 v218, v210, v210
	v_mul_f32_e32 v219, v211, v211
	v_mul_f32_e32 v220, v212, v212
	v_mul_f32_e32 v221, v213, v213
	v_mul_f32_e32 v222, v214, v214
	v_mul_f32_e32 v223, v215, v215
	v_fmamk_f32 v216, v216, 0x3dd2d3e8, v204
	v_fmamk_f32 v217, v217, 0x3dd2d3e8, v204
	v_fmamk_f32 v218, v218, 0x3dd2d3e8, v204
	v_fmamk_f32 v219, v219, 0x3dd2d3e8, v204
	v_fmamk_f32 v220, v220, 0x3dd2d3e8, v204
	v_fmamk_f32 v221, v221, 0x3dd2d3e8, v204
	v_fmamk_f32 v222, v222, 0x3dd2d3e8, v204
	v_fmamk_f32 v223, v223, 0x3dd2d3e8, v204
	v_mul_f32_e32 v216, v216, v208
	v_mul_f32_e32 v217, v217, v209
	v_mul_f32_e32 v218, v218, v210
	v_mul_f32_e32 v219, v219, v211
	v_mul_f32_e32 v220, v220, v212
	v_mul_f32_e32 v221, v221, v213
	v_mul_f32_e32 v222, v222, v214
	v_mul_f32_e32 v223, v223, v215
	v_exp_f32_e32 v216, v216
	v_exp_f32_e32 v217, v217
	v_exp_f32_e32 v218, v218
	v_exp_f32_e32 v219, v219
	v_exp_f32_e32 v220, v220
	v_exp_f32_e32 v221, v221
	v_exp_f32_e32 v222, v222
	v_exp_f32_e32 v223, v223
	v_lshlrev_b32_e32 v224, 16, v156
	v_and_b32_e32 v225, 0xffff0000, v156
	v_lshlrev_b32_e32 v226, 16, v157
	v_and_b32_e32 v227, 0xffff0000, v157
	v_lshlrev_b32_e32 v228, 16, v158
	v_and_b32_e32 v229, 0xffff0000, v158
	v_lshlrev_b32_e32 v230, 16, v159
	v_and_b32_e32 v231, 0xffff0000, v159
	v_add_f32_e32 v216, 1.0, v216
	v_add_f32_e32 v217, 1.0, v217
	v_add_f32_e32 v218, 1.0, v218
	v_add_f32_e32 v219, 1.0, v219
	v_add_f32_e32 v220, 1.0, v220
	v_add_f32_e32 v221, 1.0, v221
	v_add_f32_e32 v222, 1.0, v222
	v_add_f32_e32 v223, 1.0, v223
	v_rcp_f32_e32 v216, v216
	v_rcp_f32_e32 v217, v217
	v_rcp_f32_e32 v218, v218
	v_rcp_f32_e32 v219, v219
	v_rcp_f32_e32 v220, v220
	v_rcp_f32_e32 v221, v221
	v_rcp_f32_e32 v222, v222
	v_rcp_f32_e32 v223, v223
	s_nop 0
	v_fma_f32 v216, -v208, v216, v208
	v_fma_f32 v217, -v209, v217, v209
	v_fma_f32 v218, -v210, v218, v210
	v_fma_f32 v219, -v211, v219, v211
	v_fma_f32 v220, -v212, v220, v212
	v_fma_f32 v221, -v213, v221, v213
	v_fma_f32 v222, -v214, v222, v214
	v_fma_f32 v223, -v215, v223, v215
	v_mul_f32_e32 v216, v216, v224
	v_mul_f32_e32 v217, v217, v225
	v_mul_f32_e32 v218, v218, v226
	v_mul_f32_e32 v219, v219, v227
	v_mul_f32_e32 v220, v220, v228
	v_mul_f32_e32 v221, v221, v229
	v_mul_f32_e32 v222, v222, v230
	v_mul_f32_e32 v223, v223, v231
	v_cvt_pk_bf16_f32 v208, v216, v217
	v_cvt_pk_bf16_f32 v209, v218, v219
	v_cvt_pk_bf16_f32 v210, v220, v221
	v_cvt_pk_bf16_f32 v211, v222, v223
	global_store_dwordx4 v198, v[208:211], s[96:97] sc1
	v_mov_b32_e32 v195, v172
	v_and_b32_e32 v200, 56, v195
	v_lshrrev_b32_e32 v201, 3, v195
	v_and_b32_e32 v201, 56, v201
	v_lshl_or_b32 v200, v200, 3, v201
	v_and_b32_e32 v201, 0xfffffe07, v195
	v_or_b32_e32 v200, v200, v201
	v_cmp_lt_i32_e32 vcc, s14, v195
	s_nop 1
	v_cndmask_b32_e32 v195, v195, v200, vcc
	v_and_b32_e32 v200, 63, v195
	v_bfe_u32 v201, v195, 6, 6
	v_and_b32_e32 v202, 0xff, v195
	v_mov_b32_e32 v216, 0xff
	v_cndmask_b32_e32 v200, v202, v200, vcc
	v_cndmask_b32_e64 v216, v216, 63, vcc
	s_mov_b64 s[0:1], vcc
	v_cmp_ne_u32_e64 s[86:87], 0, v200
	v_cmp_ne_u32_e64 s[88:89], v216, v200
	v_cmp_ne_u32_e64 s[82:83], 0, v201
	v_cmp_ne_u32_e64 s[92:93], 63, v201
	v_mad_u32_u24 v197, v195, s15, v199
	s_and_b64 s[82:83], s[82:83], s[0:1]
	s_and_b64 s[92:93], s[92:93], s[0:1]
	s_and_b64 s[80:81], s[82:83], s[86:87]
	s_and_b64 s[84:85], s[82:83], s[88:89]
	s_and_b64 s[90:91], s[92:93], s[86:87]
	s_and_b64 s[94:95], s[92:93], s[88:89]
	global_load_dwordx4 v[96:99], v197, s[60:61]
	global_load_dwordx4 v[152:155], v197, s[96:97]
	v_subrev_u32_e32 v217, 0x59600, v197
	v_subrev_u32_e32 v218, 0x58000, v197
	v_subrev_u32_e32 v219, 0x56a00, v197
	v_subrev_u32_e32 v220, 0x1600, v197
	v_add_u32_e32 v221, 0x1600, v197
	v_add_u32_e32 v222, 0x56a00, v197
	v_add_u32_e32 v223, 0x58000, v197
	v_add_u32_e32 v224, 0x59600, v197
	s_nop 0
	v_cndmask_b32_e64 v217, v197, v217, s[80:81]
	v_cndmask_b32_e64 v218, v197, v218, s[82:83]
	v_cndmask_b32_e64 v219, v197, v219, s[84:85]
	v_cndmask_b32_e64 v220, v197, v220, s[86:87]
	v_cndmask_b32_e64 v221, v197, v221, s[88:89]
	v_cndmask_b32_e64 v222, v197, v222, s[90:91]
	v_cndmask_b32_e64 v223, v197, v223, s[92:93]
	v_cndmask_b32_e64 v224, v197, v224, s[94:95]
	global_load_dwordx4 v[80:83], v217, s[60:61]
	global_load_dwordx4 v[84:87], v218, s[60:61]
	global_load_dwordx4 v[88:91], v219, s[60:61]
	global_load_dwordx4 v[92:95], v220, s[60:61]
	global_load_dwordx4 v[100:103], v221, s[60:61]
	global_load_dwordx4 v[104:107], v222, s[60:61]
	global_load_dwordx4 v[108:111], v223, s[60:61]
	global_load_dwordx4 v[112:115], v224, s[60:61]
	v_add_u32_e32 v172, s12, v172
	v_mov_b32_e32 v195, v172
	v_and_b32_e32 v200, 56, v195
	v_lshrrev_b32_e32 v201, 3, v195
	v_and_b32_e32 v201, 56, v201
	v_lshl_or_b32 v200, v200, 3, v201
	v_and_b32_e32 v201, 0xfffffe07, v195
	v_or_b32_e32 v200, v200, v201
	v_cmp_lt_i32_e32 vcc, s14, v195
	s_nop 1
	v_cndmask_b32_e32 v195, v195, v200, vcc
	v_and_b32_e32 v200, 63, v195
	v_bfe_u32 v201, v195, 6, 6
	v_and_b32_e32 v202, 0xff, v195
	v_mov_b32_e32 v216, 0xff
	v_cndmask_b32_e32 v200, v202, v200, vcc
	v_cndmask_b32_e64 v216, v216, 63, vcc
	s_mov_b64 s[0:1], vcc
	v_cmp_ne_u32_e64 s[50:51], 0, v200
	v_cmp_ne_u32_e64 s[52:53], v216, v200
	v_cmp_ne_u32_e64 s[46:47], 0, v201
	v_cmp_ne_u32_e64 s[56:57], 63, v201
	v_mad_u32_u24 v198, v195, s15, v199
	s_and_b64 s[46:47], s[46:47], s[0:1]
	s_and_b64 s[56:57], s[56:57], s[0:1]
	s_and_b64 s[44:45], s[46:47], s[50:51]
	s_and_b64 s[48:49], s[46:47], s[52:53]
	s_and_b64 s[54:55], s[56:57], s[50:51]
	s_and_b64 s[58:59], s[56:57], s[52:53]
	global_load_dwordx4 v[132:135], v198, s[60:61]
	global_load_dwordx4 v[156:159], v198, s[96:97]
	v_subrev_u32_e32 v217, 0x59600, v198
	v_subrev_u32_e32 v218, 0x58000, v198
	v_subrev_u32_e32 v219, 0x56a00, v198
	v_subrev_u32_e32 v220, 0x1600, v198
	v_add_u32_e32 v221, 0x1600, v198
	v_add_u32_e32 v222, 0x56a00, v198
	v_add_u32_e32 v223, 0x58000, v198
	v_add_u32_e32 v224, 0x59600, v198
	s_nop 0
	v_cndmask_b32_e64 v217, v198, v217, s[44:45]
	v_cndmask_b32_e64 v218, v198, v218, s[46:47]
	v_cndmask_b32_e64 v219, v198, v219, s[48:49]
	v_cndmask_b32_e64 v220, v198, v220, s[50:51]
	v_cndmask_b32_e64 v221, v198, v221, s[52:53]
	v_cndmask_b32_e64 v222, v198, v222, s[54:55]
	v_cndmask_b32_e64 v223, v198, v223, s[56:57]
	v_cndmask_b32_e64 v224, v198, v224, s[58:59]
	global_load_dwordx4 v[116:119], v217, s[60:61]
	global_load_dwordx4 v[120:123], v218, s[60:61]
	global_load_dwordx4 v[124:127], v219, s[60:61]
	global_load_dwordx4 v[128:131], v220, s[60:61]
	global_load_dwordx4 v[136:139], v221, s[60:61]
	global_load_dwordx4 v[140:143], v222, s[60:61]
	global_load_dwordx4 v[144:147], v223, s[60:61]
	global_load_dwordx4 v[148:151], v224, s[60:61]
	v_add_u32_e32 v172, s12, v172
	s_waitcnt vmcnt(10)
	v_lshlrev_b32_e32 v216, 16, v96
	v_and_b32_e32 v217, 0xffff0000, v96
	v_lshlrev_b32_e32 v218, 16, v97
	v_and_b32_e32 v219, 0xffff0000, v97
	v_lshlrev_b32_e32 v220, 16, v98
	v_and_b32_e32 v221, 0xffff0000, v98
	v_lshlrev_b32_e32 v222, 16, v99
	v_and_b32_e32 v223, 0xffff0000, v99
	v_fma_f32 v208, v32, v216, v72
	v_fma_f32 v209, v33, v217, v73
	v_fma_f32 v210, v34, v218, v74
	v_fma_f32 v211, v35, v219, v75
	v_fma_f32 v212, v36, v220, v76
	v_fma_f32 v213, v37, v221, v77
	v_fma_f32 v214, v38, v222, v78
	v_fma_f32 v215, v39, v223, v79
	s_mov_b64 exec, s[80:81]
	s_cbranch_execz .Lact_t5_k0
	v_lshlrev_b32_e32 v216, 16, v80
	v_and_b32_e32 v217, 0xffff0000, v80
	v_lshlrev_b32_e32 v218, 16, v81
	v_and_b32_e32 v219, 0xffff0000, v81
	v_lshlrev_b32_e32 v220, 16, v82
	v_and_b32_e32 v221, 0xffff0000, v82
	v_lshlrev_b32_e32 v222, 16, v83
	v_and_b32_e32 v223, 0xffff0000, v83
	v_fmac_f32_e32 v208, v0, v216
	v_fmac_f32_e32 v209, v1, v217
	v_fmac_f32_e32 v210, v2, v218
	v_fmac_f32_e32 v211, v3, v219
	v_fmac_f32_e32 v212, v4, v220
	v_fmac_f32_e32 v213, v5, v221
	v_fmac_f32_e32 v214, v6, v222
	v_fmac_f32_e32 v215, v7, v223

.Lact_t6_k8:
	s_mov_b64 exec, s[38:39]
	v_mul_f32_e32 v216, v208, v208
	v_mul_f32_e32 v217, v209, v209
	v_mul_f32_e32 v218, v210, v210
	v_mul_f32_e32 v219, v211, v211
	v_mul_f32_e32 v220, v212, v212
	v_mul_f32_e32 v221, v213, v213
	v_mul_f32_e32 v222, v214, v214
	v_mul_f32_e32 v223, v215, v215
	v_fmamk_f32 v216, v216, 0x3dd2d3e8, v204
	v_fmamk_f32 v217, v217, 0x3dd2d3e8, v204
	v_fmamk_f32 v218, v218, 0x3dd2d3e8, v204
	v_fmamk_f32 v219, v219, 0x3dd2d3e8, v204
	v_fmamk_f32 v220, v220, 0x3dd2d3e8, v204
	v_fmamk_f32 v221, v221, 0x3dd2d3e8, v204
	v_fmamk_f32 v222, v222, 0x3dd2d3e8, v204
	v_fmamk_f32 v223, v223, 0x3dd2d3e8, v204
	v_mul_f32_e32 v216, v216, v208
	v_mul_f32_e32 v217, v217, v209
	v_mul_f32_e32 v218, v218, v210
	v_mul_f32_e32 v219, v219, v211
	v_mul_f32_e32 v220, v220, v212
	v_mul_f32_e32 v221, v221, v213
	v_mul_f32_e32 v222, v222, v214
	v_mul_f32_e32 v223, v223, v215
	v_exp_f32_e32 v216, v216
	v_exp_f32_e32 v217, v217
	v_exp_f32_e32 v218, v218
	v_exp_f32_e32 v219, v219
	v_exp_f32_e32 v220, v220
	v_exp_f32_e32 v221, v221
	v_exp_f32_e32 v222, v222
	v_exp_f32_e32 v223, v223
	v_lshlrev_b32_e32 v224, 16, v156
	v_and_b32_e32 v225, 0xffff0000, v156
	v_lshlrev_b32_e32 v226, 16, v157
	v_and_b32_e32 v227, 0xffff0000, v157
	v_lshlrev_b32_e32 v228, 16, v158
	v_and_b32_e32 v229, 0xffff0000, v158
	v_lshlrev_b32_e32 v230, 16, v159
	v_and_b32_e32 v231, 0xffff0000, v159
	v_add_f32_e32 v216, 1.0, v216
	v_add_f32_e32 v217, 1.0, v217
	v_add_f32_e32 v218, 1.0, v218
	v_add_f32_e32 v219, 1.0, v219
	v_add_f32_e32 v220, 1.0, v220
	v_add_f32_e32 v221, 1.0, v221
	v_add_f32_e32 v222, 1.0, v222
	v_add_f32_e32 v223, 1.0, v223
	v_rcp_f32_e32 v216, v216
	v_rcp_f32_e32 v217, v217
	v_rcp_f32_e32 v218, v218
	v_rcp_f32_e32 v219, v219
	v_rcp_f32_e32 v220, v220
	v_rcp_f32_e32 v221, v221
	v_rcp_f32_e32 v222, v222
	v_rcp_f32_e32 v223, v223
	s_nop 0
	v_fma_f32 v216, -v208, v216, v208
	v_fma_f32 v217, -v209, v217, v209
	v_fma_f32 v218, -v210, v218, v210
	v_fma_f32 v219, -v211, v219, v211
	v_fma_f32 v220, -v212, v220, v212
	v_fma_f32 v221, -v213, v221, v213
	v_fma_f32 v222, -v214, v222, v214
	v_fma_f32 v223, -v215, v223, v215
	v_mul_f32_e32 v216, v216, v224
	v_mul_f32_e32 v217, v217, v225
	v_mul_f32_e32 v218, v218, v226
	v_mul_f32_e32 v219, v219, v227
	v_mul_f32_e32 v220, v220, v228
	v_mul_f32_e32 v221, v221, v229
	v_mul_f32_e32 v222, v222, v230
	v_mul_f32_e32 v223, v223, v231
	v_cvt_pk_bf16_f32 v208, v216, v217
	v_cvt_pk_bf16_f32 v209, v218, v219
	v_cvt_pk_bf16_f32 v210, v220, v221
	v_cvt_pk_bf16_f32 v211, v222, v223
	global_store_dwordx4 v198, v[208:211], s[96:97] sc1
	v_mov_b32_e32 v195, v172
	v_and_b32_e32 v200, 56, v195
	v_lshrrev_b32_e32 v201, 3, v195
	v_and_b32_e32 v201, 56, v201
	v_lshl_or_b32 v200, v200, 3, v201
	v_and_b32_e32 v201, 0xfffffe07, v195
	v_or_b32_e32 v200, v200, v201
	v_cmp_lt_i32_e32 vcc, s14, v195
	s_nop 1
	v_cndmask_b32_e32 v195, v195, v200, vcc
	v_and_b32_e32 v200, 63, v195
	v_bfe_u32 v201, v195, 6, 6
	v_and_b32_e32 v202, 0xff, v195
	v_mov_b32_e32 v216, 0xff
	v_cndmask_b32_e32 v200, v202, v200, vcc
	v_cndmask_b32_e64 v216, v216, 63, vcc
	s_mov_b64 s[0:1], vcc
	v_cmp_ne_u32_e64 s[50:51], 0, v200
	v_cmp_ne_u32_e64 s[52:53], v216, v200
	v_cmp_ne_u32_e64 s[46:47], 0, v201
	v_cmp_ne_u32_e64 s[56:57], 63, v201
	v_mad_u32_u24 v198, v195, s15, v199
	s_and_b64 s[46:47], s[46:47], s[0:1]
	s_and_b64 s[56:57], s[56:57], s[0:1]
	s_and_b64 s[44:45], s[46:47], s[50:51]
	s_and_b64 s[48:49], s[46:47], s[52:53]
	s_and_b64 s[54:55], s[56:57], s[50:51]
	s_and_b64 s[58:59], s[56:57], s[52:53]
	global_load_dwordx4 v[132:135], v198, s[60:61]
	global_load_dwordx4 v[156:159], v198, s[96:97]
	v_subrev_u32_e32 v217, 0x59600, v198
	v_subrev_u32_e32 v218, 0x58000, v198
	v_subrev_u32_e32 v219, 0x56a00, v198
	v_subrev_u32_e32 v220, 0x1600, v198
	v_add_u32_e32 v221, 0x1600, v198
	v_add_u32_e32 v222, 0x56a00, v198
	v_add_u32_e32 v223, 0x58000, v198
	v_add_u32_e32 v224, 0x59600, v198
	s_nop 0
	v_cndmask_b32_e64 v217, v198, v217, s[44:45]
	v_cndmask_b32_e64 v218, v198, v218, s[46:47]
	v_cndmask_b32_e64 v219, v198, v219, s[48:49]
	v_cndmask_b32_e64 v220, v198, v220, s[50:51]
	v_cndmask_b32_e64 v221, v198, v221, s[52:53]
	v_cndmask_b32_e64 v222, v198, v222, s[54:55]
	v_cndmask_b32_e64 v223, v198, v223, s[56:57]
	v_cndmask_b32_e64 v224, v198, v224, s[58:59]
	global_load_dwordx4 v[116:119], v217, s[60:61]
	global_load_dwordx4 v[120:123], v218, s[60:61]
	global_load_dwordx4 v[124:127], v219, s[60:61]
	global_load_dwordx4 v[128:131], v220, s[60:61]
	global_load_dwordx4 v[136:139], v221, s[60:61]
	global_load_dwordx4 v[140:143], v222, s[60:61]
	global_load_dwordx4 v[144:147], v223, s[60:61]
	global_load_dwordx4 v[148:151], v224, s[60:61]
	v_add_u32_e32 v172, s12, v172
	s_waitcnt vmcnt(11)
	v_lshlrev_b32_e32 v216, 16, v96
	v_and_b32_e32 v217, 0xffff0000, v96
	v_lshlrev_b32_e32 v218, 16, v97
	v_and_b32_e32 v219, 0xffff0000, v97
	v_lshlrev_b32_e32 v220, 16, v98
	v_and_b32_e32 v221, 0xffff0000, v98
	v_lshlrev_b32_e32 v222, 16, v99
	v_and_b32_e32 v223, 0xffff0000, v99
	v_fma_f32 v208, v32, v216, v72
	v_fma_f32 v209, v33, v217, v73
	v_fma_f32 v210, v34, v218, v74
	v_fma_f32 v211, v35, v219, v75
	v_fma_f32 v212, v36, v220, v76
	v_fma_f32 v213, v37, v221, v77
	v_fma_f32 v214, v38, v222, v78
	v_fma_f32 v215, v39, v223, v79
	s_mov_b64 exec, s[80:81]
	s_cbranch_execz .Lact_t7_k0
	v_lshlrev_b32_e32 v216, 16, v80
	v_and_b32_e32 v217, 0xffff0000, v80
	v_lshlrev_b32_e32 v218, 16, v81
	v_and_b32_e32 v219, 0xffff0000, v81
	v_lshlrev_b32_e32 v220, 16, v82
	v_and_b32_e32 v221, 0xffff0000, v82
	v_lshlrev_b32_e32 v222, 16, v83
	v_and_b32_e32 v223, 0xffff0000, v83
	v_fmac_f32_e32 v208, v0, v216
	v_fmac_f32_e32 v209, v1, v217
	v_fmac_f32_e32 v210, v2, v218
	v_fmac_f32_e32 v211, v3, v219
	v_fmac_f32_e32 v212, v4, v220
	v_fmac_f32_e32 v213, v5, v221
	v_fmac_f32_e32 v214, v6, v222
	v_fmac_f32_e32 v215, v7, v223

.Lact_t7_k8:
	s_mov_b64 exec, s[38:39]
	v_mul_f32_e32 v216, v208, v208
	v_mul_f32_e32 v217, v209, v209
	v_mul_f32_e32 v218, v210, v210
	v_mul_f32_e32 v219, v211, v211
	v_mul_f32_e32 v220, v212, v212
	v_mul_f32_e32 v221, v213, v213
	v_mul_f32_e32 v222, v214, v214
	v_mul_f32_e32 v223, v215, v215
	v_fmamk_f32 v216, v216, 0x3dd2d3e8, v204
	v_fmamk_f32 v217, v217, 0x3dd2d3e8, v204
	v_fmamk_f32 v218, v218, 0x3dd2d3e8, v204
	v_fmamk_f32 v219, v219, 0x3dd2d3e8, v204
	v_fmamk_f32 v220, v220, 0x3dd2d3e8, v204
	v_fmamk_f32 v221, v221, 0x3dd2d3e8, v204
	v_fmamk_f32 v222, v222, 0x3dd2d3e8, v204
	v_fmamk_f32 v223, v223, 0x3dd2d3e8, v204
	v_mul_f32_e32 v216, v216, v208
	v_mul_f32_e32 v217, v217, v209
	v_mul_f32_e32 v218, v218, v210
	v_mul_f32_e32 v219, v219, v211
	v_mul_f32_e32 v220, v220, v212
	v_mul_f32_e32 v221, v221, v213
	v_mul_f32_e32 v222, v222, v214
	v_mul_f32_e32 v223, v223, v215
	v_exp_f32_e32 v216, v216
	v_exp_f32_e32 v217, v217
	v_exp_f32_e32 v218, v218
	v_exp_f32_e32 v219, v219
	v_exp_f32_e32 v220, v220
	v_exp_f32_e32 v221, v221
	v_exp_f32_e32 v222, v222
	v_exp_f32_e32 v223, v223
	v_lshlrev_b32_e32 v224, 16, v152
	v_and_b32_e32 v225, 0xffff0000, v152
	v_lshlrev_b32_e32 v226, 16, v153
	v_and_b32_e32 v227, 0xffff0000, v153
	v_lshlrev_b32_e32 v228, 16, v154
	v_and_b32_e32 v229, 0xffff0000, v154
	v_lshlrev_b32_e32 v230, 16, v155
	v_and_b32_e32 v231, 0xffff0000, v155
	v_add_f32_e32 v216, 1.0, v216
	v_add_f32_e32 v217, 1.0, v217
	v_add_f32_e32 v218, 1.0, v218
	v_add_f32_e32 v219, 1.0, v219
	v_add_f32_e32 v220, 1.0, v220
	v_add_f32_e32 v221, 1.0, v221
	v_add_f32_e32 v222, 1.0, v222
	v_add_f32_e32 v223, 1.0, v223
	v_rcp_f32_e32 v216, v216
	v_rcp_f32_e32 v217, v217
	v_rcp_f32_e32 v218, v218
	v_rcp_f32_e32 v219, v219
	v_rcp_f32_e32 v220, v220
	v_rcp_f32_e32 v221, v221
	v_rcp_f32_e32 v222, v222
	v_rcp_f32_e32 v223, v223
	s_nop 0
	v_fma_f32 v216, -v208, v216, v208
	v_fma_f32 v217, -v209, v217, v209
	v_fma_f32 v218, -v210, v218, v210
	v_fma_f32 v219, -v211, v219, v211
	v_fma_f32 v220, -v212, v220, v212
	v_fma_f32 v221, -v213, v221, v213
	v_fma_f32 v222, -v214, v222, v214
	v_fma_f32 v223, -v215, v223, v215
	v_mul_f32_e32 v216, v216, v224
	v_mul_f32_e32 v217, v217, v225
	v_mul_f32_e32 v218, v218, v226
	v_mul_f32_e32 v219, v219, v227
	v_mul_f32_e32 v220, v220, v228
	v_mul_f32_e32 v221, v221, v229
	v_mul_f32_e32 v222, v222, v230
	v_mul_f32_e32 v223, v223, v231
	v_cvt_pk_bf16_f32 v208, v216, v217
	v_cvt_pk_bf16_f32 v209, v218, v219
	v_cvt_pk_bf16_f32 v210, v220, v221
	v_cvt_pk_bf16_f32 v211, v222, v223
	global_store_dwordx4 v197, v[208:211], s[96:97] sc1
	s_sub_u32 s8, s8, 1
	s_cmp_lg_u32 s8, 0
	s_cbranch_scc1 .Lact_lat_loop
	s_waitcnt vmcnt(1)
	v_lshlrev_b32_e32 v216, 16, v132
	v_and_b32_e32 v217, 0xffff0000, v132
	v_lshlrev_b32_e32 v218, 16, v133
	v_and_b32_e32 v219, 0xffff0000, v133
	v_lshlrev_b32_e32 v220, 16, v134
	v_and_b32_e32 v221, 0xffff0000, v134
	v_lshlrev_b32_e32 v222, 16, v135
	v_and_b32_e32 v223, 0xffff0000, v135
	v_fma_f32 v208, v32, v216, v72
	v_fma_f32 v209, v33, v217, v73
	v_fma_f32 v210, v34, v218, v74
	v_fma_f32 v211, v35, v219, v75
	v_fma_f32 v212, v36, v220, v76
	v_fma_f32 v213, v37, v221, v77
	v_fma_f32 v214, v38, v222, v78
	v_fma_f32 v215, v39, v223, v79
	s_mov_b64 exec, s[44:45]
	s_cbranch_execz .Lact_t8_k0
	v_lshlrev_b32_e32 v216, 16, v116
	v_and_b32_e32 v217, 0xffff0000, v116
	v_lshlrev_b32_e32 v218, 16, v117
	v_and_b32_e32 v219, 0xffff0000, v117
	v_lshlrev_b32_e32 v220, 16, v118
	v_and_b32_e32 v221, 0xffff0000, v118
	v_lshlrev_b32_e32 v222, 16, v119
	v_and_b32_e32 v223, 0xffff0000, v119
	v_fmac_f32_e32 v208, v0, v216
	v_fmac_f32_e32 v209, v1, v217
	v_fmac_f32_e32 v210, v2, v218
	v_fmac_f32_e32 v211, v3, v219
	v_fmac_f32_e32 v212, v4, v220
	v_fmac_f32_e32 v213, v5, v221
	v_fmac_f32_e32 v214, v6, v222
	v_fmac_f32_e32 v215, v7, v223

.Lact_t8_k8:
	s_mov_b64 exec, s[38:39]
	v_mul_f32_e32 v216, v208, v208
	v_mul_f32_e32 v217, v209, v209
	v_mul_f32_e32 v218, v210, v210
	v_mul_f32_e32 v219, v211, v211
	v_mul_f32_e32 v220, v212, v212
	v_mul_f32_e32 v221, v213, v213
	v_mul_f32_e32 v222, v214, v214
	v_mul_f32_e32 v223, v215, v215
	v_fmamk_f32 v216, v216, 0x3dd2d3e8, v204
	v_fmamk_f32 v217, v217, 0x3dd2d3e8, v204
	v_fmamk_f32 v218, v218, 0x3dd2d3e8, v204
	v_fmamk_f32 v219, v219, 0x3dd2d3e8, v204
	v_fmamk_f32 v220, v220, 0x3dd2d3e8, v204
	v_fmamk_f32 v221, v221, 0x3dd2d3e8, v204
	v_fmamk_f32 v222, v222, 0x3dd2d3e8, v204
	v_fmamk_f32 v223, v223, 0x3dd2d3e8, v204
	v_mul_f32_e32 v216, v216, v208
	v_mul_f32_e32 v217, v217, v209
	v_mul_f32_e32 v218, v218, v210
	v_mul_f32_e32 v219, v219, v211
	v_mul_f32_e32 v220, v220, v212
	v_mul_f32_e32 v221, v221, v213
	v_mul_f32_e32 v222, v222, v214
	v_mul_f32_e32 v223, v223, v215
	v_exp_f32_e32 v216, v216
	v_exp_f32_e32 v217, v217
	v_exp_f32_e32 v218, v218
	v_exp_f32_e32 v219, v219
	v_exp_f32_e32 v220, v220
	v_exp_f32_e32 v221, v221
	v_exp_f32_e32 v222, v222
	v_exp_f32_e32 v223, v223
	v_lshlrev_b32_e32 v224, 16, v156
	v_and_b32_e32 v225, 0xffff0000, v156
	v_lshlrev_b32_e32 v226, 16, v157
	v_and_b32_e32 v227, 0xffff0000, v157
	v_lshlrev_b32_e32 v228, 16, v158
	v_and_b32_e32 v229, 0xffff0000, v158
	v_lshlrev_b32_e32 v230, 16, v159
	v_and_b32_e32 v231, 0xffff0000, v159
	v_add_f32_e32 v216, 1.0, v216
	v_add_f32_e32 v217, 1.0, v217
	v_add_f32_e32 v218, 1.0, v218
	v_add_f32_e32 v219, 1.0, v219
	v_add_f32_e32 v220, 1.0, v220
	v_add_f32_e32 v221, 1.0, v221
	v_add_f32_e32 v222, 1.0, v222
	v_add_f32_e32 v223, 1.0, v223
	v_rcp_f32_e32 v216, v216
	v_rcp_f32_e32 v217, v217
	v_rcp_f32_e32 v218, v218
	v_rcp_f32_e32 v219, v219
	v_rcp_f32_e32 v220, v220
	v_rcp_f32_e32 v221, v221
	v_rcp_f32_e32 v222, v222
	v_rcp_f32_e32 v223, v223
	s_nop 0
	v_fma_f32 v216, -v208, v216, v208
	v_fma_f32 v217, -v209, v217, v209
	v_fma_f32 v218, -v210, v218, v210
	v_fma_f32 v219, -v211, v219, v211
	v_fma_f32 v220, -v212, v220, v212
	v_fma_f32 v221, -v213, v221, v213
	v_fma_f32 v222, -v214, v222, v214
	v_fma_f32 v223, -v215, v223, v215
	v_mul_f32_e32 v216, v216, v224
	v_mul_f32_e32 v217, v217, v225
	v_mul_f32_e32 v218, v218, v226
	v_mul_f32_e32 v219, v219, v227
	v_mul_f32_e32 v220, v220, v228
	v_mul_f32_e32 v221, v221, v229
	v_mul_f32_e32 v222, v222, v230
	v_mul_f32_e32 v223, v223, v231
	v_cvt_pk_bf16_f32 v208, v216, v217
	v_cvt_pk_bf16_f32 v209, v218, v219
	v_cvt_pk_bf16_f32 v210, v220, v221
	v_cvt_pk_bf16_f32 v211, v222, v223
	global_store_dwordx4 v198, v[208:211], s[96:97] sc1
	v_cmp_gt_i32_e32 vcc, s13, v172
	s_and_b64 exec, exec, vcc
	s_cbranch_execz .Lact_done
	s_mov_b64 s[38:39], exec
	v_mov_b32_e32 v195, v172
	v_and_b32_e32 v200, 56, v195
	v_lshrrev_b32_e32 v201, 3, v195
	v_and_b32_e32 v201, 56, v201
	v_lshl_or_b32 v200, v200, 3, v201
	v_and_b32_e32 v201, 0xfffffe07, v195
	v_or_b32_e32 v200, v200, v201
	v_cmp_lt_i32_e32 vcc, s14, v195
	s_nop 1
	v_cndmask_b32_e32 v195, v195, v200, vcc
	v_and_b32_e32 v200, 63, v195
	v_bfe_u32 v201, v195, 6, 6
	v_and_b32_e32 v202, 0xff, v195
	v_mov_b32_e32 v216, 0xff
	v_cndmask_b32_e32 v200, v202, v200, vcc
	v_cndmask_b32_e64 v216, v216, 63, vcc
	s_mov_b64 s[0:1], vcc
	v_cmp_ne_u32_e64 s[86:87], 0, v200
	v_cmp_ne_u32_e64 s[88:89], v216, v200
	v_cmp_ne_u32_e64 s[82:83], 0, v201
	v_cmp_ne_u32_e64 s[92:93], 63, v201
	v_mad_u32_u24 v197, v195, s15, v199
	s_and_b64 s[82:83], s[82:83], s[0:1]
	s_and_b64 s[92:93], s[92:93], s[0:1]
	s_and_b64 s[80:81], s[82:83], s[86:87]
	s_and_b64 s[84:85], s[82:83], s[88:89]
	s_and_b64 s[90:91], s[92:93], s[86:87]
	s_and_b64 s[94:95], s[92:93], s[88:89]
	global_load_dwordx4 v[96:99], v197, s[60:61]
	global_load_dwordx4 v[152:155], v197, s[96:97]
	v_subrev_u32_e32 v217, 0x59600, v197
	v_subrev_u32_e32 v218, 0x58000, v197
	v_subrev_u32_e32 v219, 0x56a00, v197
	v_subrev_u32_e32 v220, 0x1600, v197
	v_add_u32_e32 v221, 0x1600, v197
	v_add_u32_e32 v222, 0x56a00, v197
	v_add_u32_e32 v223, 0x58000, v197
	v_add_u32_e32 v224, 0x59600, v197
	s_nop 0
	v_cndmask_b32_e64 v217, v197, v217, s[80:81]
	v_cndmask_b32_e64 v218, v197, v218, s[82:83]
	v_cndmask_b32_e64 v219, v197, v219, s[84:85]
	v_cndmask_b32_e64 v220, v197, v220, s[86:87]
	v_cndmask_b32_e64 v221, v197, v221, s[88:89]
	v_cndmask_b32_e64 v222, v197, v222, s[90:91]
	v_cndmask_b32_e64 v223, v197, v223, s[92:93]
	v_cndmask_b32_e64 v224, v197, v224, s[94:95]
	global_load_dwordx4 v[80:83], v217, s[60:61]
	global_load_dwordx4 v[84:87], v218, s[60:61]
	global_load_dwordx4 v[88:91], v219, s[60:61]
	global_load_dwordx4 v[92:95], v220, s[60:61]
	global_load_dwordx4 v[100:103], v221, s[60:61]
	global_load_dwordx4 v[104:107], v222, s[60:61]
	global_load_dwordx4 v[108:111], v223, s[60:61]
	global_load_dwordx4 v[112:115], v224, s[60:61]
	s_waitcnt vmcnt(0)
	v_lshlrev_b32_e32 v216, 16, v96
	v_and_b32_e32 v217, 0xffff0000, v96
	v_lshlrev_b32_e32 v218, 16, v97
	v_and_b32_e32 v219, 0xffff0000, v97
	v_lshlrev_b32_e32 v220, 16, v98
	v_and_b32_e32 v221, 0xffff0000, v98
	v_lshlrev_b32_e32 v222, 16, v99
	v_and_b32_e32 v223, 0xffff0000, v99
	v_fma_f32 v208, v32, v216, v72
	v_fma_f32 v209, v33, v217, v73
	v_fma_f32 v210, v34, v218, v74
	v_fma_f32 v211, v35, v219, v75
	v_fma_f32 v212, v36, v220, v76
	v_fma_f32 v213, v37, v221, v77
	v_fma_f32 v214, v38, v222, v78
	v_fma_f32 v215, v39, v223, v79
	s_mov_b64 exec, s[80:81]
	s_cbranch_execz .Lact_t9_k0
	v_lshlrev_b32_e32 v216, 16, v80
	v_and_b32_e32 v217, 0xffff0000, v80
	v_lshlrev_b32_e32 v218, 16, v81
	v_and_b32_e32 v219, 0xffff0000, v81
	v_lshlrev_b32_e32 v220, 16, v82
	v_and_b32_e32 v221, 0xffff0000, v82
	v_lshlrev_b32_e32 v222, 16, v83
	v_and_b32_e32 v223, 0xffff0000, v83
	v_fmac_f32_e32 v208, v0, v216
	v_fmac_f32_e32 v209, v1, v217
	v_fmac_f32_e32 v210, v2, v218
	v_fmac_f32_e32 v211, v3, v219
	v_fmac_f32_e32 v212, v4, v220
	v_fmac_f32_e32 v213, v5, v221
	v_fmac_f32_e32 v214, v6, v222
	v_fmac_f32_e32 v215, v7, v223

.Lact_t9_k8:
	s_mov_b64 exec, s[38:39]
	v_mul_f32_e32 v216, v208, v208
	v_mul_f32_e32 v217, v209, v209
	v_mul_f32_e32 v218, v210, v210
	v_mul_f32_e32 v219, v211, v211
	v_mul_f32_e32 v220, v212, v212
	v_mul_f32_e32 v221, v213, v213
	v_mul_f32_e32 v222, v214, v214
	v_mul_f32_e32 v223, v215, v215
	v_fmamk_f32 v216, v216, 0x3dd2d3e8, v204
	v_fmamk_f32 v217, v217, 0x3dd2d3e8, v204
	v_fmamk_f32 v218, v218, 0x3dd2d3e8, v204
	v_fmamk_f32 v219, v219, 0x3dd2d3e8, v204
	v_fmamk_f32 v220, v220, 0x3dd2d3e8, v204
	v_fmamk_f32 v221, v221, 0x3dd2d3e8, v204
	v_fmamk_f32 v222, v222, 0x3dd2d3e8, v204
	v_fmamk_f32 v223, v223, 0x3dd2d3e8, v204
	v_mul_f32_e32 v216, v216, v208
	v_mul_f32_e32 v217, v217, v209
	v_mul_f32_e32 v218, v218, v210
	v_mul_f32_e32 v219, v219, v211
	v_mul_f32_e32 v220, v220, v212
	v_mul_f32_e32 v221, v221, v213
	v_mul_f32_e32 v222, v222, v214
	v_mul_f32_e32 v223, v223, v215
	v_exp_f32_e32 v216, v216
	v_exp_f32_e32 v217, v217
	v_exp_f32_e32 v218, v218
	v_exp_f32_e32 v219, v219
	v_exp_f32_e32 v220, v220
	v_exp_f32_e32 v221, v221
	v_exp_f32_e32 v222, v222
	v_exp_f32_e32 v223, v223
	v_lshlrev_b32_e32 v224, 16, v152
	v_and_b32_e32 v225, 0xffff0000, v152
	v_lshlrev_b32_e32 v226, 16, v153
	v_and_b32_e32 v227, 0xffff0000, v153
	v_lshlrev_b32_e32 v228, 16, v154
	v_and_b32_e32 v229, 0xffff0000, v154
	v_lshlrev_b32_e32 v230, 16, v155
	v_and_b32_e32 v231, 0xffff0000, v155
	v_add_f32_e32 v216, 1.0, v216
	v_add_f32_e32 v217, 1.0, v217
	v_add_f32_e32 v218, 1.0, v218
	v_add_f32_e32 v219, 1.0, v219
	v_add_f32_e32 v220, 1.0, v220
	v_add_f32_e32 v221, 1.0, v221
	v_add_f32_e32 v222, 1.0, v222
	v_add_f32_e32 v223, 1.0, v223
	v_rcp_f32_e32 v216, v216
	v_rcp_f32_e32 v217, v217
	v_rcp_f32_e32 v218, v218
	v_rcp_f32_e32 v219, v219
	v_rcp_f32_e32 v220, v220
	v_rcp_f32_e32 v221, v221
	v_rcp_f32_e32 v222, v222
	v_rcp_f32_e32 v223, v223
	s_nop 0
	v_fma_f32 v216, -v208, v216, v208
	v_fma_f32 v217, -v209, v217, v209
	v_fma_f32 v218, -v210, v218, v210
	v_fma_f32 v219, -v211, v219, v211
	v_fma_f32 v220, -v212, v220, v212
	v_fma_f32 v221, -v213, v221, v213
	v_fma_f32 v222, -v214, v222, v214
	v_fma_f32 v223, -v215, v223, v215
	v_mul_f32_e32 v216, v216, v224
	v_mul_f32_e32 v217, v217, v225
	v_mul_f32_e32 v218, v218, v226
	v_mul_f32_e32 v219, v219, v227
	v_mul_f32_e32 v220, v220, v228
	v_mul_f32_e32 v221, v221, v229
	v_mul_f32_e32 v222, v222, v230
	v_mul_f32_e32 v223, v223, v231
	v_cvt_pk_bf16_f32 v208, v216, v217
	v_cvt_pk_bf16_f32 v209, v218, v219
	v_cvt_pk_bf16_f32 v210, v220, v221
	v_cvt_pk_bf16_f32 v211, v222, v223
	global_store_dwordx4 v197, v[208:211], s[96:97] sc1

.Lfz_start:
	s_waitcnt vmcnt(0) lgkmcnt(0)
	v_lshrrev_b32_e32 v232, 6, v177
	v_and_b32_e32 v233, 63, v177
	v_readfirstlane_b32 s8, v232
	v_readlane_b32 s40, v255, 4
	v_readlane_b32 s41, v255, 5
	v_readlane_b32 s42, v253, 1
	v_readlane_b32 s43, v253, 2
	v_readlane_b32 s44, v252, 63
	v_readlane_b32 s45, v253, 0
	s_nop 3
	s_cmp_gt_u32 s8, 3
	s_cbranch_scc1 .Lfz_nosync
	s_barrier
.Lfz_nosync:
	s_barrier
	s_and_b32 s9, s72, 7
	s_lshl_b32 s9, s9, 3
	s_bfe_u32 s11, s72, 0x30003
	s_or_b32 s9, s9, s11
	s_lshr_b32 s10, s72, 6
	v_and_b32_e32 v234, 15, v233
	v_lshrrev_b32_e32 v235, 4, v233
	s_and_b32 s11, s8, 3
	s_lshr_b32 s12, s8, 2
	s_lshl_b32 s12, s12, 6
	v_add_u32_e32 v236, s12, v234
	s_lshl_b32 s12, s11, 5
	v_lshl_add_u32 v237, v235, 2, s12
	v_lshl_add_u32 v230, v236, 4, v235
	s_lshl_b32 s12, s11, 2
	v_add_u32_e32 v230, s12, v230
	v_lshlrev_b32_e32 v230, 2, v230
	s_lshl_b32 s12, s10, 8
	v_add_u32_e32 v229, s12, v237
	v_lshlrev_b32_e32 v229, 2, v229
	s_lshl_b32 s12, s9, 8
	v_add_u32_e32 v228, s12, v236
	v_lshl_add_u32 v228, v228, 12, v229
	s_sub_u32 s11, s9, 32
	s_lshr_b32 s11, s11, 4
	s_add_u32 s11, s11, 1
	s_cmp_lt_u32 s9, 32
	s_cselect_b32 s11, 0, s11
	s_mul_i32 s11, s11, 0x6000
	s_add_u32 s11, s11, 0x5000
	s_add_u32 s46, s40, s11
	s_addc_u32 s47, s41, 0
	s_add_u32 s50, s40, 0xf984000
	s_addc_u32 s51, s41, 0
	global_load_dwordx4 v[144:147], v229, s[46:47]
	global_load_dwordx4 v[148:151], v229, s[46:47] offset:64
	global_load_dwordx4 v[152:155], v229, s[46:47] offset:512
	global_load_dwordx4 v[156:159], v229, s[46:47] offset:576
	global_load_dwordx4 v[212:215], v229, s[44:45]
	global_load_dwordx4 v[216:219], v229, s[44:45] offset:64
	global_load_dwordx4 v[220:223], v229, s[44:45] offset:512
	global_load_dwordx4 v[224:227], v229, s[44:45] offset:576
	s_add_u32 s48, s42, 0x0
	s_addc_u32 s49, s43, 0
	global_load_dwordx4 v[180:183], v228, s[48:49]
	global_load_dwordx4 v[184:187], v228, s[48:49] offset:64
	global_load_dwordx4 v[188:191], v228, s[48:49] offset:512
	global_load_dwordx4 v[192:195], v228, s[48:49] offset:576
	s_add_u32 s48, s42, 0x10000
	s_addc_u32 s49, s43, 0
	global_load_dwordx4 v[196:199], v228, s[48:49]
	global_load_dwordx4 v[200:203], v228, s[48:49] offset:64
	global_load_dwordx4 v[204:207], v228, s[48:49] offset:512
	global_load_dwordx4 v[208:211], v228, s[48:49] offset:576
	s_waitcnt vmcnt(4)
	v_pk_fma_f32 v[140:141], v[140:141], v[144:145], v[180:181]
	v_pk_fma_f32 v[142:143], v[142:143], v[146:147], v[182:183]
	v_pk_fma_f32 v[136:137], v[136:137], v[148:149], v[184:185]
	v_pk_fma_f32 v[138:139], v[138:139], v[150:151], v[186:187]
	v_pk_fma_f32 v[132:133], v[132:133], v[152:153], v[188:189]
	v_pk_fma_f32 v[134:135], v[134:135], v[154:155], v[190:191]
	v_pk_fma_f32 v[128:129], v[128:129], v[156:157], v[192:193]
	v_pk_fma_f32 v[130:131], v[130:131], v[158:159], v[194:195]
	v_mul_f32_e32 v232, v140, v140
	v_fmac_f32_e32 v232, v141, v141
	v_fmac_f32_e32 v232, v142, v142
	v_fmac_f32_e32 v232, v143, v143
	v_fmac_f32_e32 v232, v136, v136
	v_fmac_f32_e32 v232, v137, v137
	v_fmac_f32_e32 v232, v138, v138
	v_fmac_f32_e32 v232, v139, v139
	v_fmac_f32_e32 v232, v132, v132
	v_fmac_f32_e32 v232, v133, v133
	v_fmac_f32_e32 v232, v134, v134
	v_fmac_f32_e32 v232, v135, v135
	v_fmac_f32_e32 v232, v128, v128
	v_fmac_f32_e32 v232, v129, v129
	v_fmac_f32_e32 v232, v130, v130
	v_fmac_f32_e32 v232, v131, v131
	ds_write_b32 v230, v232 offset:0
	s_add_u32 s48, s42, 0x20000
	s_addc_u32 s49, s43, 0
	global_load_dwordx4 v[180:183], v228, s[48:49]
	global_load_dwordx4 v[184:187], v228, s[48:49] offset:64
	global_load_dwordx4 v[188:191], v228, s[48:49] offset:512
	global_load_dwordx4 v[192:195], v228, s[48:49] offset:576
	s_waitcnt vmcnt(4)
	v_pk_fma_f32 v[124:125], v[124:125], v[144:145], v[196:197]
	v_pk_fma_f32 v[126:127], v[126:127], v[146:147], v[198:199]
	v_pk_fma_f32 v[120:121], v[120:121], v[148:149], v[200:201]
	v_pk_fma_f32 v[122:123], v[122:123], v[150:151], v[202:203]
	v_pk_fma_f32 v[116:117], v[116:117], v[152:153], v[204:205]
	v_pk_fma_f32 v[118:119], v[118:119], v[154:155], v[206:207]
	v_pk_fma_f32 v[112:113], v[112:113], v[156:157], v[208:209]
	v_pk_fma_f32 v[114:115], v[114:115], v[158:159], v[210:211]
	v_mul_f32_e32 v232, v124, v124
	v_fmac_f32_e32 v232, v125, v125
	v_fmac_f32_e32 v232, v126, v126
	v_fmac_f32_e32 v232, v127, v127
	v_fmac_f32_e32 v232, v120, v120
	v_fmac_f32_e32 v232, v121, v121
	v_fmac_f32_e32 v232, v122, v122
	v_fmac_f32_e32 v232, v123, v123
	v_fmac_f32_e32 v232, v116, v116
	v_fmac_f32_e32 v232, v117, v117
	v_fmac_f32_e32 v232, v118, v118
	v_fmac_f32_e32 v232, v119, v119
	v_fmac_f32_e32 v232, v112, v112
	v_fmac_f32_e32 v232, v113, v113
	v_fmac_f32_e32 v232, v114, v114
	v_fmac_f32_e32 v232, v115, v115
	ds_write_b32 v230, v232 offset:1024
	s_add_u32 s48, s42, 0x30000
	s_addc_u32 s49, s43, 0
	global_load_dwordx4 v[196:199], v228, s[48:49]
	global_load_dwordx4 v[200:203], v228, s[48:49] offset:64
	global_load_dwordx4 v[204:207], v228, s[48:49] offset:512
	global_load_dwordx4 v[208:211], v228, s[48:49] offset:576
	s_waitcnt vmcnt(4)
	v_pk_fma_f32 v[108:109], v[108:109], v[144:145], v[180:181]
	v_pk_fma_f32 v[110:111], v[110:111], v[146:147], v[182:183]
	v_pk_fma_f32 v[104:105], v[104:105], v[148:149], v[184:185]
	v_pk_fma_f32 v[106:107], v[106:107], v[150:151], v[186:187]
	v_pk_fma_f32 v[96:97], v[96:97], v[152:153], v[188:189]
	v_pk_fma_f32 v[98:99], v[98:99], v[154:155], v[190:191]
	v_pk_fma_f32 v[88:89], v[88:89], v[156:157], v[192:193]
	v_pk_fma_f32 v[90:91], v[90:91], v[158:159], v[194:195]
	v_mul_f32_e32 v232, v108, v108
	v_fmac_f32_e32 v232, v109, v109
	v_fmac_f32_e32 v232, v110, v110
	v_fmac_f32_e32 v232, v111, v111
	v_fmac_f32_e32 v232, v104, v104
	v_fmac_f32_e32 v232, v105, v105
	v_fmac_f32_e32 v232, v106, v106
	v_fmac_f32_e32 v232, v107, v107
	v_fmac_f32_e32 v232, v96, v96
	v_fmac_f32_e32 v232, v97, v97
	v_fmac_f32_e32 v232, v98, v98
	v_fmac_f32_e32 v232, v99, v99
	v_fmac_f32_e32 v232, v88, v88
	v_fmac_f32_e32 v232, v89, v89
	v_fmac_f32_e32 v232, v90, v90
	v_fmac_f32_e32 v232, v91, v91
	ds_write_b32 v230, v232 offset:2048
	s_add_u32 s48, s42, 0x80000
	s_addc_u32 s49, s43, 0
	global_load_dwordx4 v[180:183], v228, s[48:49]
	global_load_dwordx4 v[184:187], v228, s[48:49] offset:64
	global_load_dwordx4 v[188:191], v228, s[48:49] offset:512
	global_load_dwordx4 v[192:195], v228, s[48:49] offset:576
	s_waitcnt vmcnt(4)
	v_pk_fma_f32 v[76:77], v[76:77], v[144:145], v[196:197]
	v_pk_fma_f32 v[78:79], v[78:79], v[146:147], v[198:199]
	v_pk_fma_f32 v[72:73], v[72:73], v[148:149], v[200:201]
	v_pk_fma_f32 v[74:75], v[74:75], v[150:151], v[202:203]
	v_pk_fma_f32 v[68:69], v[68:69], v[152:153], v[204:205]
	v_pk_fma_f32 v[70:71], v[70:71], v[154:155], v[206:207]
	v_pk_fma_f32 v[64:65], v[64:65], v[156:157], v[208:209]
	v_pk_fma_f32 v[66:67], v[66:67], v[158:159], v[210:211]
	v_mul_f32_e32 v232, v76, v76
	v_fmac_f32_e32 v232, v77, v77
	v_fmac_f32_e32 v232, v78, v78
	v_fmac_f32_e32 v232, v79, v79
	v_fmac_f32_e32 v232, v72, v72
	v_fmac_f32_e32 v232, v73, v73
	v_fmac_f32_e32 v232, v74, v74
	v_fmac_f32_e32 v232, v75, v75
	v_fmac_f32_e32 v232, v68, v68
	v_fmac_f32_e32 v232, v69, v69
	v_fmac_f32_e32 v232, v70, v70
	v_fmac_f32_e32 v232, v71, v71
	v_fmac_f32_e32 v232, v64, v64
	v_fmac_f32_e32 v232, v65, v65
	v_fmac_f32_e32 v232, v66, v66
	v_fmac_f32_e32 v232, v67, v67
	ds_write_b32 v230, v232 offset:3072
	s_add_u32 s48, s42, 0x90000
	s_addc_u32 s49, s43, 0
	global_load_dwordx4 v[196:199], v228, s[48:49]
	global_load_dwordx4 v[200:203], v228, s[48:49] offset:64
	global_load_dwordx4 v[204:207], v228, s[48:49] offset:512
	global_load_dwordx4 v[208:211], v228, s[48:49] offset:576
	s_waitcnt vmcnt(4)
	v_pk_fma_f32 v[60:61], v[60:61], v[144:145], v[180:181]
	v_pk_fma_f32 v[62:63], v[62:63], v[146:147], v[182:183]
	v_pk_fma_f32 v[56:57], v[56:57], v[148:149], v[184:185]
	v_pk_fma_f32 v[58:59], v[58:59], v[150:151], v[186:187]
	v_pk_fma_f32 v[52:53], v[52:53], v[152:153], v[188:189]
	v_pk_fma_f32 v[54:55], v[54:55], v[154:155], v[190:191]
	v_pk_fma_f32 v[48:49], v[48:49], v[156:157], v[192:193]
	v_pk_fma_f32 v[50:51], v[50:51], v[158:159], v[194:195]
	v_mul_f32_e32 v232, v60, v60
	v_fmac_f32_e32 v232, v61, v61
	v_fmac_f32_e32 v232, v62, v62
	v_fmac_f32_e32 v232, v63, v63
	v_fmac_f32_e32 v232, v56, v56
	v_fmac_f32_e32 v232, v57, v57
	v_fmac_f32_e32 v232, v58, v58
	v_fmac_f32_e32 v232, v59, v59
	v_fmac_f32_e32 v232, v52, v52
	v_fmac_f32_e32 v232, v53, v53
	v_fmac_f32_e32 v232, v54, v54
	v_fmac_f32_e32 v232, v55, v55
	v_fmac_f32_e32 v232, v48, v48
	v_fmac_f32_e32 v232, v49, v49
	v_fmac_f32_e32 v232, v50, v50
	v_fmac_f32_e32 v232, v51, v51
	ds_write_b32 v230, v232 offset:8192
	s_add_u32 s48, s42, 0xa0000
	s_addc_u32 s49, s43, 0
	global_load_dwordx4 v[180:183], v228, s[48:49]
	global_load_dwordx4 v[184:187], v228, s[48:49] offset:64
	global_load_dwordx4 v[188:191], v228, s[48:49] offset:512
	global_load_dwordx4 v[192:195], v228, s[48:49] offset:576
	s_waitcnt vmcnt(4)
	v_pk_fma_f32 v[44:45], v[44:45], v[144:145], v[196:197]
	v_pk_fma_f32 v[46:47], v[46:47], v[146:147], v[198:199]
	v_pk_fma_f32 v[40:41], v[40:41], v[148:149], v[200:201]
	v_pk_fma_f32 v[42:43], v[42:43], v[150:151], v[202:203]
	v_pk_fma_f32 v[36:37], v[36:37], v[152:153], v[204:205]
	v_pk_fma_f32 v[38:39], v[38:39], v[154:155], v[206:207]
	v_pk_fma_f32 v[32:33], v[32:33], v[156:157], v[208:209]
	v_pk_fma_f32 v[34:35], v[34:35], v[158:159], v[210:211]
	v_mul_f32_e32 v232, v44, v44
	v_fmac_f32_e32 v232, v45, v45
	v_fmac_f32_e32 v232, v46, v46
	v_fmac_f32_e32 v232, v47, v47
	v_fmac_f32_e32 v232, v40, v40
	v_fmac_f32_e32 v232, v41, v41
	v_fmac_f32_e32 v232, v42, v42
	v_fmac_f32_e32 v232, v43, v43
	v_fmac_f32_e32 v232, v36, v36
	v_fmac_f32_e32 v232, v37, v37
	v_fmac_f32_e32 v232, v38, v38
	v_fmac_f32_e32 v232, v39, v39
	v_fmac_f32_e32 v232, v32, v32
	v_fmac_f32_e32 v232, v33, v33
	v_fmac_f32_e32 v232, v34, v34
	v_fmac_f32_e32 v232, v35, v35
	ds_write_b32 v230, v232 offset:9216
	s_add_u32 s48, s42, 0xb0000
	s_addc_u32 s49, s43, 0
	global_load_dwordx4 v[196:199], v228, s[48:49]
	global_load_dwordx4 v[200:203], v228, s[48:49] offset:64
	global_load_dwordx4 v[204:207], v228, s[48:49] offset:512
	global_load_dwordx4 v[208:211], v228, s[48:49] offset:576
	s_waitcnt vmcnt(4)
	v_pk_fma_f32 v[28:29], v[28:29], v[144:145], v[180:181]
	v_pk_fma_f32 v[30:31], v[30:31], v[146:147], v[182:183]
	v_pk_fma_f32 v[24:25], v[24:25], v[148:149], v[184:185]
	v_pk_fma_f32 v[26:27], v[26:27], v[150:151], v[186:187]
	v_pk_fma_f32 v[16:17], v[16:17], v[152:153], v[188:189]
	v_pk_fma_f32 v[18:19], v[18:19], v[154:155], v[190:191]
	v_pk_fma_f32 v[8:9], v[8:9], v[156:157], v[192:193]
	v_pk_fma_f32 v[10:11], v[10:11], v[158:159], v[194:195]
	v_mul_f32_e32 v232, v28, v28
	v_fmac_f32_e32 v232, v29, v29
	v_fmac_f32_e32 v232, v30, v30
	v_fmac_f32_e32 v232, v31, v31
	v_fmac_f32_e32 v232, v24, v24
	v_fmac_f32_e32 v232, v25, v25
	v_fmac_f32_e32 v232, v26, v26
	v_fmac_f32_e32 v232, v27, v27
	v_fmac_f32_e32 v232, v16, v16
	v_fmac_f32_e32 v232, v17, v17
	v_fmac_f32_e32 v232, v18, v18
	v_fmac_f32_e32 v232, v19, v19
	v_fmac_f32_e32 v232, v8, v8
	v_fmac_f32_e32 v232, v9, v9
	v_fmac_f32_e32 v232, v10, v10
	v_fmac_f32_e32 v232, v11, v11
	ds_write_b32 v230, v232 offset:10240
	s_waitcnt vmcnt(0)
	v_pk_fma_f32 v[20:21], v[20:21], v[144:145], v[196:197]
	v_pk_fma_f32 v[22:23], v[22:23], v[146:147], v[198:199]
	v_pk_fma_f32 v[12:13], v[12:13], v[148:149], v[200:201]
	v_pk_fma_f32 v[14:15], v[14:15], v[150:151], v[202:203]
	v_pk_fma_f32 v[4:5], v[4:5], v[152:153], v[204:205]
	v_pk_fma_f32 v[6:7], v[6:7], v[154:155], v[206:207]
	v_pk_fma_f32 v[0:1], v[0:1], v[156:157], v[208:209]
	v_pk_fma_f32 v[2:3], v[2:3], v[158:159], v[210:211]
	v_mul_f32_e32 v232, v20, v20
	v_fmac_f32_e32 v232, v21, v21
	v_fmac_f32_e32 v232, v22, v22
	v_fmac_f32_e32 v232, v23, v23
	v_fmac_f32_e32 v232, v12, v12
	v_fmac_f32_e32 v232, v13, v13
	v_fmac_f32_e32 v232, v14, v14
	v_fmac_f32_e32 v232, v15, v15
	v_fmac_f32_e32 v232, v4, v4
	v_fmac_f32_e32 v232, v5, v5
	v_fmac_f32_e32 v232, v6, v6
	v_fmac_f32_e32 v232, v7, v7
	v_fmac_f32_e32 v232, v0, v0
	v_fmac_f32_e32 v232, v1, v1
	v_fmac_f32_e32 v232, v2, v2
	v_fmac_f32_e32 v232, v3, v3
	ds_write_b32 v230, v232 offset:11264
	s_waitcnt lgkmcnt(0)
	s_barrier
	v_cmp_gt_u32_e32 vcc, 0x100, v177
	s_and_saveexec_b64 s[0:1], vcc
	s_cbranch_execz .Lfz_nored
	v_lshlrev_b32_e32 v233, 6, v177
	ds_read_b128 v[236:239], v233
	ds_read_b128 v[240:243], v233 offset:16
	ds_read_b128 v[244:247], v233 offset:32
	ds_read_b128 v[248:251], v233 offset:48
	s_lshl_b32 s11, s9, 8
	v_add_u32_e32 v234, s11, v177
	v_lshlrev_b32_e32 v234, 4, v234
	s_lshl_b32 s11, s10, 2
	v_add_u32_e32 v234, s11, v234
	s_waitcnt lgkmcnt(0)
	v_add_f32_e32 v236, v236, v237
	v_add_f32_e32 v236, v236, v238
	v_add_f32_e32 v236, v236, v239
	v_add_f32_e32 v236, v236, v240
	v_add_f32_e32 v236, v236, v241
	v_add_f32_e32 v236, v236, v242
	v_add_f32_e32 v236, v236, v243
	v_add_f32_e32 v236, v236, v244
	v_add_f32_e32 v236, v236, v245
	v_add_f32_e32 v236, v236, v246
	v_add_f32_e32 v236, v236, v247
	v_add_f32_e32 v236, v236, v248
	v_add_f32_e32 v236, v236, v249
	v_add_f32_e32 v236, v236, v250
	v_add_f32_e32 v236, v236, v251
	global_store_dword v234, v236, s[50:51]
.Lfz_nored:
	s_or_b64 exec, exec, s[0:1]
	s_waitcnt vmcnt(0) lgkmcnt(0)
	s_barrier
	v_cmp_eq_u32_e32 vcc, 0, v177
	s_and_saveexec_b64 s[0:1], vcc
	s_cbranch_execz .Lfz_bar_end_a
	s_add_u32 s98, s98, 1
	v_mov_b32_e32 v237, 0x26c00
	ds_read2_b32 v[238:239], v237 offset1:1
	v_mov_b32_e32 v232, s99
	v_mov_b32_e32 v233, 1
	global_atomic_add v234, v232, v233, s[100:101] sc0
	v_add_u32_e32 v232, 0x1000, v232
	v_mov_b32_e32 v240, 0x2480
	s_waitcnt vmcnt(0) lgkmcnt(0)
	v_add_u32_e32 v234, 1, v234
	v_mul_lo_u32 v235, v238, s98
	v_mul_lo_u32 v239, v239, s98
	v_cmp_eq_u32_e32 vcc, v234, v235
	s_and_saveexec_b64 s[4:5], vcc
	s_cbranch_execz .Lfz_skip_a
	buffer_wbl2 sc1
	s_waitcnt vmcnt(0)
	global_atomic_add v240, v233, s[100:101]
	global_atomic_add v240, v233, s[100:101] offset:256
	global_atomic_add v240, v233, s[100:101] offset:512
	global_atomic_add v240, v233, s[100:101] offset:768
	global_atomic_add v240, v233, s[100:101] offset:1024
	global_atomic_add v240, v233, s[100:101] offset:1280
	global_atomic_add v240, v233, s[100:101] offset:1536
	global_atomic_add v240, v233, s[100:101] offset:1792
	global_atomic_add v240, v233, s[100:101] offset:2048
	global_atomic_add v240, v233, s[100:101] offset:2304
	global_atomic_add v240, v233, s[100:101] offset:2560
	global_atomic_add v240, v233, s[100:101] offset:2816
	global_atomic_add v240, v233, s[100:101] offset:3072
	global_atomic_add v240, v233, s[100:101] offset:3328
	global_atomic_add v240, v233, s[100:101] offset:3584
	global_atomic_add v240, v233, s[100:101] offset:3840

.Lfz_spin_a:
	s_sleep 1
	global_load_dword v234, v232, s[100:101] sc1
	s_waitcnt vmcnt(0)
	v_cmp_lt_u32_e32 vcc, v234, v239
	s_cbranch_vccnz .Lfz_spin_a
	buffer_inv sc1
	s_waitcnt vmcnt(0)
.Lfz_bar_end_a:
	s_or_b64 exec, exec, s[0:1]
	s_barrier
	v_lshrrev_b32_e32 v232, 12, v228
	v_lshlrev_b32_e32 v232, 4, v232
	v_add_u32_e32 v233, 0x0, v232
	v_add_u32_e32 v234, 0x100, v232
	v_add_u32_e32 v235, 0x200, v232
	v_add_u32_e32 v236, 0x300, v232
	v_add_u32_e32 v237, 0x800, v232
	v_add_u32_e32 v238, 0x900, v232
	v_add_u32_e32 v239, 0xa00, v232
	v_add_u32_e32 v240, 0xb00, v232
	global_load_dwordx4 v[180:183], v233, s[50:51]
	global_load_dwordx4 v[184:187], v234, s[50:51]
	global_load_dwordx4 v[188:191], v235, s[50:51]
	global_load_dwordx4 v[192:195], v236, s[50:51]
	global_load_dwordx4 v[196:199], v237, s[50:51]
	global_load_dwordx4 v[200:203], v238, s[50:51]
	global_load_dwordx4 v[204:207], v239, s[50:51]
	global_load_dwordx4 v[208:211], v240, s[50:51]
	s_waitcnt vmcnt(0)
	v_mov_b32_e32 v242, 0x3a800000
	v_mov_b32_e32 v243, 0x358637bd
	v_add_f32_e32 v160, v180, v181
	v_add_f32_e32 v160, v160, v182
	v_add_f32_e32 v160, v160, v183
	v_fma_f32 v160, v160, v242, v243
	v_add_f32_e32 v161, v184, v185
	v_add_f32_e32 v161, v161, v186
	v_add_f32_e32 v161, v161, v187
	v_fma_f32 v161, v161, v242, v243
	v_add_f32_e32 v162, v188, v189
	v_add_f32_e32 v162, v162, v190
	v_add_f32_e32 v162, v162, v191
	v_fma_f32 v162, v162, v242, v243
	v_add_f32_e32 v163, v192, v193
	v_add_f32_e32 v163, v163, v194
	v_add_f32_e32 v163, v163, v195
	v_fma_f32 v163, v163, v242, v243
	v_add_f32_e32 v164, v196, v197
	v_add_f32_e32 v164, v164, v198
	v_add_f32_e32 v164, v164, v199
	v_fma_f32 v164, v164, v242, v243
	v_add_f32_e32 v165, v200, v201
	v_add_f32_e32 v165, v165, v202
	v_add_f32_e32 v165, v165, v203
	v_fma_f32 v165, v165, v242, v243
	v_add_f32_e32 v166, v204, v205
	v_add_f32_e32 v166, v166, v206
	v_add_f32_e32 v166, v166, v207
	v_fma_f32 v166, v166, v242, v243
	v_add_f32_e32 v167, v208, v209
	v_add_f32_e32 v167, v167, v210
	v_add_f32_e32 v167, v167, v211
	v_fma_f32 v167, v167, v242, v243
	v_rsq_f32_e32 v160, v160
	v_rsq_f32_e32 v161, v161
	v_rsq_f32_e32 v162, v162
	v_rsq_f32_e32 v163, v163
	v_rsq_f32_e32 v164, v164
	v_rsq_f32_e32 v165, v165
	v_rsq_f32_e32 v166, v166
	v_rsq_f32_e32 v167, v167
	s_nop 0
	s_add_u32 s48, s42, 0x0
	s_addc_u32 s49, s43, 0
	v_mul_f32_e32 v140, v140, v160
	v_mul_f32_e32 v141, v141, v160
	v_mul_f32_e32 v142, v142, v160
	v_mul_f32_e32 v143, v143, v160
	v_pk_mul_f32 v[140:141], v[140:141], v[212:213]
	v_pk_mul_f32 v[142:143], v[142:143], v[214:215]
	v_mul_f32_e32 v136, v136, v160
	v_mul_f32_e32 v137, v137, v160
	v_mul_f32_e32 v138, v138, v160
	v_mul_f32_e32 v139, v139, v160
	v_pk_mul_f32 v[136:137], v[136:137], v[216:217]
	v_pk_mul_f32 v[138:139], v[138:139], v[218:219]
	v_mul_f32_e32 v132, v132, v160
	v_mul_f32_e32 v133, v133, v160
	v_mul_f32_e32 v134, v134, v160
	v_mul_f32_e32 v135, v135, v160
	v_pk_mul_f32 v[132:133], v[132:133], v[220:221]
	v_pk_mul_f32 v[134:135], v[134:135], v[222:223]
	v_mul_f32_e32 v128, v128, v160
	v_mul_f32_e32 v129, v129, v160
	v_mul_f32_e32 v130, v130, v160
	v_mul_f32_e32 v131, v131, v160
	v_pk_mul_f32 v[128:129], v[128:129], v[224:225]
	v_pk_mul_f32 v[130:131], v[130:131], v[226:227]
	global_store_dwordx4 v228, v[140:143], s[48:49]
	global_store_dwordx4 v228, v[136:139], s[48:49] offset:64
	global_store_dwordx4 v228, v[132:135], s[48:49] offset:512
	global_store_dwordx4 v228, v[128:131], s[48:49] offset:576
	s_add_u32 s48, s42, 0x10000
	s_addc_u32 s49, s43, 0
	v_mul_f32_e32 v124, v124, v161
	v_mul_f32_e32 v125, v125, v161
	v_mul_f32_e32 v126, v126, v161
	v_mul_f32_e32 v127, v127, v161
	v_pk_mul_f32 v[124:125], v[124:125], v[212:213]
	v_pk_mul_f32 v[126:127], v[126:127], v[214:215]
	v_mul_f32_e32 v120, v120, v161
	v_mul_f32_e32 v121, v121, v161
	v_mul_f32_e32 v122, v122, v161
	v_mul_f32_e32 v123, v123, v161
	v_pk_mul_f32 v[120:121], v[120:121], v[216:217]
	v_pk_mul_f32 v[122:123], v[122:123], v[218:219]
	v_mul_f32_e32 v116, v116, v161
	v_mul_f32_e32 v117, v117, v161
	v_mul_f32_e32 v118, v118, v161
	v_mul_f32_e32 v119, v119, v161
	v_pk_mul_f32 v[116:117], v[116:117], v[220:221]
	v_pk_mul_f32 v[118:119], v[118:119], v[222:223]
	v_mul_f32_e32 v112, v112, v161
	v_mul_f32_e32 v113, v113, v161
	v_mul_f32_e32 v114, v114, v161
	v_mul_f32_e32 v115, v115, v161
	v_pk_mul_f32 v[112:113], v[112:113], v[224:225]
	v_pk_mul_f32 v[114:115], v[114:115], v[226:227]
	global_store_dwordx4 v228, v[124:127], s[48:49]
	global_store_dwordx4 v228, v[120:123], s[48:49] offset:64
	global_store_dwordx4 v228, v[116:119], s[48:49] offset:512
	global_store_dwordx4 v228, v[112:115], s[48:49] offset:576
	s_add_u32 s48, s42, 0x20000
	s_addc_u32 s49, s43, 0
	v_mul_f32_e32 v108, v108, v162
	v_mul_f32_e32 v109, v109, v162
	v_mul_f32_e32 v110, v110, v162
	v_mul_f32_e32 v111, v111, v162
	v_pk_mul_f32 v[108:109], v[108:109], v[212:213]
	v_pk_mul_f32 v[110:111], v[110:111], v[214:215]
	v_mul_f32_e32 v104, v104, v162
	v_mul_f32_e32 v105, v105, v162
	v_mul_f32_e32 v106, v106, v162
	v_mul_f32_e32 v107, v107, v162
	v_pk_mul_f32 v[104:105], v[104:105], v[216:217]
	v_pk_mul_f32 v[106:107], v[106:107], v[218:219]
	v_mul_f32_e32 v96, v96, v162
	v_mul_f32_e32 v97, v97, v162
	v_mul_f32_e32 v98, v98, v162
	v_mul_f32_e32 v99, v99, v162
	v_pk_mul_f32 v[96:97], v[96:97], v[220:221]
	v_pk_mul_f32 v[98:99], v[98:99], v[222:223]
	v_mul_f32_e32 v88, v88, v162
	v_mul_f32_e32 v89, v89, v162
	v_mul_f32_e32 v90, v90, v162
	v_mul_f32_e32 v91, v91, v162
	v_pk_mul_f32 v[88:89], v[88:89], v[224:225]
	v_pk_mul_f32 v[90:91], v[90:91], v[226:227]
	global_store_dwordx4 v228, v[108:111], s[48:49]
	global_store_dwordx4 v228, v[104:107], s[48:49] offset:64
	global_store_dwordx4 v228, v[96:99], s[48:49] offset:512
	global_store_dwordx4 v228, v[88:91], s[48:49] offset:576
	s_add_u32 s48, s42, 0x30000
	s_addc_u32 s49, s43, 0
	v_mul_f32_e32 v76, v76, v163
	v_mul_f32_e32 v77, v77, v163
	v_mul_f32_e32 v78, v78, v163
	v_mul_f32_e32 v79, v79, v163
	v_pk_mul_f32 v[76:77], v[76:77], v[212:213]
	v_pk_mul_f32 v[78:79], v[78:79], v[214:215]
	v_mul_f32_e32 v72, v72, v163
	v_mul_f32_e32 v73, v73, v163
	v_mul_f32_e32 v74, v74, v163
	v_mul_f32_e32 v75, v75, v163
	v_pk_mul_f32 v[72:73], v[72:73], v[216:217]
	v_pk_mul_f32 v[74:75], v[74:75], v[218:219]
	v_mul_f32_e32 v68, v68, v163
	v_mul_f32_e32 v69, v69, v163
	v_mul_f32_e32 v70, v70, v163
	v_mul_f32_e32 v71, v71, v163
	v_pk_mul_f32 v[68:69], v[68:69], v[220:221]
	v_pk_mul_f32 v[70:71], v[70:71], v[222:223]
	v_mul_f32_e32 v64, v64, v163
	v_mul_f32_e32 v65, v65, v163
	v_mul_f32_e32 v66, v66, v163
	v_mul_f32_e32 v67, v67, v163
	v_pk_mul_f32 v[64:65], v[64:65], v[224:225]
	v_pk_mul_f32 v[66:67], v[66:67], v[226:227]
	global_store_dwordx4 v228, v[76:79], s[48:49]
	global_store_dwordx4 v228, v[72:75], s[48:49] offset:64
	global_store_dwordx4 v228, v[68:71], s[48:49] offset:512
	global_store_dwordx4 v228, v[64:67], s[48:49] offset:576
	s_add_u32 s48, s42, 0x80000
	s_addc_u32 s49, s43, 0
	v_mul_f32_e32 v60, v60, v164
	v_mul_f32_e32 v61, v61, v164
	v_mul_f32_e32 v62, v62, v164
	v_mul_f32_e32 v63, v63, v164
	v_pk_mul_f32 v[60:61], v[60:61], v[212:213]
	v_pk_mul_f32 v[62:63], v[62:63], v[214:215]
	v_mul_f32_e32 v56, v56, v164
	v_mul_f32_e32 v57, v57, v164
	v_mul_f32_e32 v58, v58, v164
	v_mul_f32_e32 v59, v59, v164
	v_pk_mul_f32 v[56:57], v[56:57], v[216:217]
	v_pk_mul_f32 v[58:59], v[58:59], v[218:219]
	v_mul_f32_e32 v52, v52, v164
	v_mul_f32_e32 v53, v53, v164
	v_mul_f32_e32 v54, v54, v164
	v_mul_f32_e32 v55, v55, v164
	v_pk_mul_f32 v[52:53], v[52:53], v[220:221]
	v_pk_mul_f32 v[54:55], v[54:55], v[222:223]
	v_mul_f32_e32 v48, v48, v164
	v_mul_f32_e32 v49, v49, v164
	v_mul_f32_e32 v50, v50, v164
	v_mul_f32_e32 v51, v51, v164
	v_pk_mul_f32 v[48:49], v[48:49], v[224:225]
	v_pk_mul_f32 v[50:51], v[50:51], v[226:227]
	global_store_dwordx4 v228, v[60:63], s[48:49]
	global_store_dwordx4 v228, v[56:59], s[48:49] offset:64
	global_store_dwordx4 v228, v[52:55], s[48:49] offset:512
	global_store_dwordx4 v228, v[48:51], s[48:49] offset:576
	s_add_u32 s48, s42, 0x90000
	s_addc_u32 s49, s43, 0
	v_mul_f32_e32 v44, v44, v165
	v_mul_f32_e32 v45, v45, v165
	v_mul_f32_e32 v46, v46, v165
	v_mul_f32_e32 v47, v47, v165
	v_pk_mul_f32 v[44:45], v[44:45], v[212:213]
	v_pk_mul_f32 v[46:47], v[46:47], v[214:215]
	v_mul_f32_e32 v40, v40, v165
	v_mul_f32_e32 v41, v41, v165
	v_mul_f32_e32 v42, v42, v165
	v_mul_f32_e32 v43, v43, v165
	v_pk_mul_f32 v[40:41], v[40:41], v[216:217]
	v_pk_mul_f32 v[42:43], v[42:43], v[218:219]
	v_mul_f32_e32 v36, v36, v165
	v_mul_f32_e32 v37, v37, v165
	v_mul_f32_e32 v38, v38, v165
	v_mul_f32_e32 v39, v39, v165
	v_pk_mul_f32 v[36:37], v[36:37], v[220:221]
	v_pk_mul_f32 v[38:39], v[38:39], v[222:223]
	v_mul_f32_e32 v32, v32, v165
	v_mul_f32_e32 v33, v33, v165
	v_mul_f32_e32 v34, v34, v165
	v_mul_f32_e32 v35, v35, v165
	v_pk_mul_f32 v[32:33], v[32:33], v[224:225]
	v_pk_mul_f32 v[34:35], v[34:35], v[226:227]
	global_store_dwordx4 v228, v[44:47], s[48:49]
	global_store_dwordx4 v228, v[40:43], s[48:49] offset:64
	global_store_dwordx4 v228, v[36:39], s[48:49] offset:512
	global_store_dwordx4 v228, v[32:35], s[48:49] offset:576
	s_add_u32 s48, s42, 0xa0000
	s_addc_u32 s49, s43, 0
	v_mul_f32_e32 v28, v28, v166
	v_mul_f32_e32 v29, v29, v166
	v_mul_f32_e32 v30, v30, v166
	v_mul_f32_e32 v31, v31, v166
	v_pk_mul_f32 v[28:29], v[28:29], v[212:213]
	v_pk_mul_f32 v[30:31], v[30:31], v[214:215]
	v_mul_f32_e32 v24, v24, v166
	v_mul_f32_e32 v25, v25, v166
	v_mul_f32_e32 v26, v26, v166
	v_mul_f32_e32 v27, v27, v166
	v_pk_mul_f32 v[24:25], v[24:25], v[216:217]
	v_pk_mul_f32 v[26:27], v[26:27], v[218:219]
	v_mul_f32_e32 v16, v16, v166
	v_mul_f32_e32 v17, v17, v166
	v_mul_f32_e32 v18, v18, v166
	v_mul_f32_e32 v19, v19, v166
	v_pk_mul_f32 v[16:17], v[16:17], v[220:221]
	v_pk_mul_f32 v[18:19], v[18:19], v[222:223]
	v_mul_f32_e32 v8, v8, v166
	v_mul_f32_e32 v9, v9, v166
	v_mul_f32_e32 v10, v10, v166
	v_mul_f32_e32 v11, v11, v166
	v_pk_mul_f32 v[8:9], v[8:9], v[224:225]
	v_pk_mul_f32 v[10:11], v[10:11], v[226:227]
	global_store_dwordx4 v228, v[28:31], s[48:49]
	global_store_dwordx4 v228, v[24:27], s[48:49] offset:64
	global_store_dwordx4 v228, v[16:19], s[48:49] offset:512
	global_store_dwordx4 v228, v[8:11], s[48:49] offset:576
	s_add_u32 s48, s42, 0xb0000
	s_addc_u32 s49, s43, 0
	v_mul_f32_e32 v20, v20, v167
	v_mul_f32_e32 v21, v21, v167
	v_mul_f32_e32 v22, v22, v167
	v_mul_f32_e32 v23, v23, v167
	v_pk_mul_f32 v[20:21], v[20:21], v[212:213]
	v_pk_mul_f32 v[22:23], v[22:23], v[214:215]
	v_mul_f32_e32 v12, v12, v167
	v_mul_f32_e32 v13, v13, v167
	v_mul_f32_e32 v14, v14, v167
	v_mul_f32_e32 v15, v15, v167
	v_pk_mul_f32 v[12:13], v[12:13], v[216:217]
	v_pk_mul_f32 v[14:15], v[14:15], v[218:219]
	v_mul_f32_e32 v4, v4, v167
	v_mul_f32_e32 v5, v5, v167
	v_mul_f32_e32 v6, v6, v167
	v_mul_f32_e32 v7, v7, v167
	v_pk_mul_f32 v[4:5], v[4:5], v[220:221]
	v_pk_mul_f32 v[6:7], v[6:7], v[222:223]
	v_mul_f32_e32 v0, v0, v167
	v_mul_f32_e32 v1, v1, v167
	v_mul_f32_e32 v2, v2, v167
	v_mul_f32_e32 v3, v3, v167
	v_pk_mul_f32 v[0:1], v[0:1], v[224:225]
	v_pk_mul_f32 v[2:3], v[2:3], v[226:227]
	global_store_dwordx4 v228, v[20:23], s[48:49]
	global_store_dwordx4 v228, v[12:15], s[48:49] offset:64
	global_store_dwordx4 v228, v[4:7], s[48:49] offset:512
	global_store_dwordx4 v228, v[0:3], s[48:49] offset:576
